# cv46 + light (2-piece) load segments of the GEMM K-loops issue their LDS-DMA loads before the ds_read fragment loads; every M0 write keeps one wait state before its LDS-DMA
# baseline (speedup 1.0000x reference)
.LBB0_306:
	s_add_u32 s38, s36, 0xfff80080
	s_addc_u32 s39, s37, -1
	s_add_i32 s45, 0, 0x10000
	s_cmp_eq_u32 s27, 28
	s_cselect_b32 s43, s9, s39
	s_cselect_b32 s42, s14, s38
	v_add_u32_e32 v34, s45, v170
	s_cselect_b32 s39, s16, s26
	s_cselect_b32 s38, s17, s25
	s_add_i32 s47, 0, 0x14000
	s_add_i32 m0, s35, 0xc000
	s_nop 0
	global_load_lds_dwordx4 v152, s[36:37]
	s_add_i32 m0, s35, 0xe000
	s_nop 0
	global_load_lds_dwordx4 v156, s[36:37]
	ds_read_b128 v[160:163], v34
	ds_read_b128 v[164:167], v34 offset:1024
	ds_read_b128 v[174:177], v34 offset:2048
	ds_read_b128 v[184:187], v34 offset:3072
	v_add_u32_e32 v34, s47, v170
	ds_read_b128 v[188:191], v34
	ds_read_b128 v[192:195], v34 offset:1024
	ds_read_b128 v[196:199], v34 offset:2048
	ds_read_b128 v[200:203], v34 offset:3072
	ds_read_b128 v[214:217], v173
	ds_read_b128 v[218:221], v173 offset:1024
	ds_read_b128 v[222:225], v173 offset:2048
	ds_read_b128 v[226:229], v173 offset:3072
	ds_read_b128 v[230:233], v173 offset:4096
	ds_read_b128 v[234:237], v173 offset:5120
	ds_read_b128 v[238:241], v173 offset:6144
	ds_read_b128 v[242:245], v173 offset:7168
	s_waitcnt vmcnt(8)
	s_waitcnt lgkmcnt(0)
	s_barrier
	s_setprio 1
	s_waitcnt lgkmcnt(0)
	v_mfma_f32_16x16x32_bf16 v[132:135], v[160:163], v[214:217], v[132:135]
	v_mfma_f32_16x16x32_bf16 v[128:131], v[174:177], v[214:217], v[128:131]
	v_mfma_f32_16x16x32_bf16 v[116:119], v[160:163], v[222:225], v[116:119]
	v_mfma_f32_16x16x32_bf16 v[112:115], v[174:177], v[222:225], v[112:115]
	v_mfma_f32_16x16x32_bf16 v[100:103], v[160:163], v[230:233], v[100:103]
	v_mfma_f32_16x16x32_bf16 v[96:99], v[174:177], v[230:233], v[96:99]
	v_mfma_f32_16x16x32_bf16 v[84:87], v[160:163], v[238:241], v[84:87]
	v_mfma_f32_16x16x32_bf16 v[80:83], v[174:177], v[238:241], v[80:83]
	v_mfma_f32_16x16x32_bf16 v[132:135], v[164:167], v[218:221], v[132:135]
	v_mfma_f32_16x16x32_bf16 v[128:131], v[184:187], v[218:221], v[128:131]
	v_mfma_f32_16x16x32_bf16 v[116:119], v[164:167], v[226:229], v[116:119]
	v_mfma_f32_16x16x32_bf16 v[112:115], v[184:187], v[226:229], v[112:115]
	v_mfma_f32_16x16x32_bf16 v[100:103], v[164:167], v[234:237], v[100:103]
	v_mfma_f32_16x16x32_bf16 v[96:99], v[184:187], v[234:237], v[96:99]
	v_mfma_f32_16x16x32_bf16 v[84:87], v[164:167], v[242:245], v[84:87]
	v_mfma_f32_16x16x32_bf16 v[80:83], v[184:187], v[242:245], v[80:83]
	s_setprio 0
	s_setprio 1
	v_mfma_f32_16x16x32_bf16 v[124:127], v[188:191], v[214:217], v[124:127]
	v_mfma_f32_16x16x32_bf16 v[120:123], v[196:199], v[214:217], v[120:123]
	v_mfma_f32_16x16x32_bf16 v[108:111], v[188:191], v[222:225], v[108:111]
	v_mfma_f32_16x16x32_bf16 v[104:107], v[196:199], v[222:225], v[104:107]
	v_mfma_f32_16x16x32_bf16 v[92:95], v[188:191], v[230:233], v[92:95]
	v_mfma_f32_16x16x32_bf16 v[88:91], v[196:199], v[230:233], v[88:91]
	v_mfma_f32_16x16x32_bf16 v[76:79], v[188:191], v[238:241], v[76:79]
	v_mfma_f32_16x16x32_bf16 v[72:75], v[196:199], v[238:241], v[72:75]
	v_mfma_f32_16x16x32_bf16 v[124:127], v[192:195], v[218:221], v[124:127]
	v_mfma_f32_16x16x32_bf16 v[120:123], v[200:203], v[218:221], v[120:123]
	v_mfma_f32_16x16x32_bf16 v[108:111], v[192:195], v[226:229], v[108:111]
	v_mfma_f32_16x16x32_bf16 v[104:107], v[200:203], v[226:229], v[104:107]
	v_mfma_f32_16x16x32_bf16 v[92:95], v[192:195], v[234:237], v[92:95]
	v_mfma_f32_16x16x32_bf16 v[88:91], v[200:203], v[234:237], v[88:91]
	v_mfma_f32_16x16x32_bf16 v[76:79], v[192:195], v[242:245], v[76:79]
	v_mfma_f32_16x16x32_bf16 v[72:75], v[200:203], v[242:245], v[72:75]
	s_setprio 0
	s_barrier
	s_add_u32 s98, s38, s22
	s_addc_u32 s99, s39, s23
	s_add_u32 s100, s42, s22
	s_addc_u32 s101, s43, s23
	s_add_i32 s45, s45, s53
	s_mov_b32 m0, s45
	ds_read_b128 v[214:217], v173 offset:16384
	ds_read_b128 v[218:221], v173 offset:17408
	ds_read_b128 v[222:225], v173 offset:18432
	ds_read_b128 v[226:229], v173 offset:19456
	ds_read_b128 v[230:233], v173 offset:20480
	ds_read_b128 v[234:237], v173 offset:21504
	ds_read_b128 v[238:241], v173 offset:22528
	ds_read_b128 v[242:245], v173 offset:23552
	global_load_lds_dwordx4 v136, s[38:39]
	s_add_i32 m0, s45, 0x2000
	s_add_u32 s70, s38, 0x80000
	s_addc_u32 s71, s39, 0
	s_add_i32 s45, s47, s53
	global_load_lds_dwordx4 v140, s[38:39]
	s_mov_b32 m0, s45
	s_nop 0
	global_load_lds_dwordx4 v136, s[70:71]
	s_add_i32 m0, s45, 0x2000
	s_nop 0
	global_load_lds_dwordx4 v140, s[70:71]
	s_mov_b32 m0, s35
	s_nop 0
	global_load_lds_dwordx4 v14, s[42:43]
	s_mov_b32 m0, s54
	s_nop 0
	global_load_lds_dwordx4 v138, s[42:43]
	s_waitcnt vmcnt(8)
	s_waitcnt lgkmcnt(0)
	s_barrier
	s_setprio 1
	s_waitcnt lgkmcnt(0)
	v_mfma_f32_16x16x32_bf16 v[68:71], v[160:163], v[214:217], v[68:71]
	v_mfma_f32_16x16x32_bf16 v[64:67], v[174:177], v[214:217], v[64:67]
	v_mfma_f32_16x16x32_bf16 v[52:55], v[160:163], v[222:225], v[52:55]
	v_mfma_f32_16x16x32_bf16 v[48:51], v[174:177], v[222:225], v[48:51]
	v_mfma_f32_16x16x32_bf16 v[36:39], v[160:163], v[230:233], v[36:39]
	v_mfma_f32_16x16x32_bf16 v[30:33], v[174:177], v[230:233], v[30:33]
	v_mfma_f32_16x16x32_bf16 v[18:21], v[160:163], v[238:241], v[18:21]
	v_mfma_f32_16x16x32_bf16 v[10:13], v[174:177], v[238:241], v[10:13]
	v_mfma_f32_16x16x32_bf16 v[68:71], v[164:167], v[218:221], v[68:71]
	v_mfma_f32_16x16x32_bf16 v[64:67], v[184:187], v[218:221], v[64:67]
	v_mfma_f32_16x16x32_bf16 v[52:55], v[164:167], v[226:229], v[52:55]
	v_mfma_f32_16x16x32_bf16 v[48:51], v[184:187], v[226:229], v[48:51]
	v_mfma_f32_16x16x32_bf16 v[36:39], v[164:167], v[234:237], v[36:39]
	v_mfma_f32_16x16x32_bf16 v[30:33], v[184:187], v[234:237], v[30:33]
	v_mfma_f32_16x16x32_bf16 v[18:21], v[164:167], v[242:245], v[18:21]
	v_mfma_f32_16x16x32_bf16 v[10:13], v[184:187], v[242:245], v[10:13]
	s_setprio 0
	s_setprio 1
	v_mfma_f32_16x16x32_bf16 v[60:63], v[188:191], v[214:217], v[60:63]
	v_mfma_f32_16x16x32_bf16 v[56:59], v[196:199], v[214:217], v[56:59]
	v_mfma_f32_16x16x32_bf16 v[44:47], v[188:191], v[222:225], v[44:47]
	v_mfma_f32_16x16x32_bf16 v[40:43], v[196:199], v[222:225], v[40:43]
	v_mfma_f32_16x16x32_bf16 v[26:29], v[188:191], v[230:233], v[26:29]
	v_mfma_f32_16x16x32_bf16 v[22:25], v[196:199], v[230:233], v[22:25]
	v_mfma_f32_16x16x32_bf16 v[6:9], v[188:191], v[238:241], v[6:9]
	v_mfma_f32_16x16x32_bf16 v[2:5], v[196:199], v[238:241], v[2:5]
	v_mfma_f32_16x16x32_bf16 v[60:63], v[192:195], v[218:221], v[60:63]
	v_mfma_f32_16x16x32_bf16 v[56:59], v[200:203], v[218:221], v[56:59]
	v_mfma_f32_16x16x32_bf16 v[44:47], v[192:195], v[226:229], v[44:47]
	v_mfma_f32_16x16x32_bf16 v[40:43], v[200:203], v[226:229], v[40:43]
	v_mfma_f32_16x16x32_bf16 v[26:29], v[192:195], v[234:237], v[26:29]
	v_mfma_f32_16x16x32_bf16 v[22:25], v[200:203], v[234:237], v[22:25]
	v_mfma_f32_16x16x32_bf16 v[6:9], v[192:195], v[242:245], v[6:9]
	v_mfma_f32_16x16x32_bf16 v[2:5], v[200:203], v[242:245], v[2:5]
	s_setprio 0
	s_barrier
	s_add_i32 s45, 0, 0x18000
	v_add_u32_e32 v34, s45, v170
	s_add_i32 s47, 0, 0x1c000
	s_add_u32 s42, s42, 0x80000
	s_addc_u32 s43, s43, 0
	s_mov_b32 m0, s55
	s_nop 0
	global_load_lds_dwordx4 v14, s[42:43]
	s_mov_b32 m0, s60
	s_nop 0
	global_load_lds_dwordx4 v138, s[42:43]
	ds_read_b128 v[160:163], v34
	ds_read_b128 v[164:167], v34 offset:1024
	ds_read_b128 v[174:177], v34 offset:2048
	ds_read_b128 v[184:187], v34 offset:3072
	v_add_u32_e32 v34, s47, v170
	ds_read_b128 v[188:191], v34
	ds_read_b128 v[192:195], v34 offset:1024
	ds_read_b128 v[196:199], v34 offset:2048
	ds_read_b128 v[200:203], v34 offset:3072
	ds_read_b128 v[214:217], v173 offset:32768
	ds_read_b128 v[218:221], v173 offset:33792
	ds_read_b128 v[222:225], v173 offset:34816
	ds_read_b128 v[226:229], v173 offset:35840
	ds_read_b128 v[230:233], v173 offset:36864
	ds_read_b128 v[234:237], v173 offset:37888
	ds_read_b128 v[238:241], v173 offset:38912
	ds_read_b128 v[242:245], v173 offset:39936
	s_waitcnt vmcnt(8)
	s_waitcnt lgkmcnt(0)
	s_barrier
	s_setprio 1
	s_waitcnt lgkmcnt(0)
	v_mfma_f32_16x16x32_bf16 v[132:135], v[160:163], v[214:217], v[132:135]
	v_mfma_f32_16x16x32_bf16 v[128:131], v[174:177], v[214:217], v[128:131]
	v_mfma_f32_16x16x32_bf16 v[116:119], v[160:163], v[222:225], v[116:119]
	v_mfma_f32_16x16x32_bf16 v[112:115], v[174:177], v[222:225], v[112:115]
	v_mfma_f32_16x16x32_bf16 v[100:103], v[160:163], v[230:233], v[100:103]
	v_mfma_f32_16x16x32_bf16 v[96:99], v[174:177], v[230:233], v[96:99]
	v_mfma_f32_16x16x32_bf16 v[84:87], v[160:163], v[238:241], v[84:87]
	v_mfma_f32_16x16x32_bf16 v[80:83], v[174:177], v[238:241], v[80:83]
	v_mfma_f32_16x16x32_bf16 v[132:135], v[164:167], v[218:221], v[132:135]
	v_mfma_f32_16x16x32_bf16 v[128:131], v[184:187], v[218:221], v[128:131]
	v_mfma_f32_16x16x32_bf16 v[116:119], v[164:167], v[226:229], v[116:119]
	v_mfma_f32_16x16x32_bf16 v[112:115], v[184:187], v[226:229], v[112:115]
	v_mfma_f32_16x16x32_bf16 v[100:103], v[164:167], v[234:237], v[100:103]
	v_mfma_f32_16x16x32_bf16 v[96:99], v[184:187], v[234:237], v[96:99]
	v_mfma_f32_16x16x32_bf16 v[84:87], v[164:167], v[242:245], v[84:87]
	v_mfma_f32_16x16x32_bf16 v[80:83], v[184:187], v[242:245], v[80:83]
	s_setprio 0
	s_setprio 1
	v_mfma_f32_16x16x32_bf16 v[124:127], v[188:191], v[214:217], v[124:127]
	v_mfma_f32_16x16x32_bf16 v[120:123], v[196:199], v[214:217], v[120:123]
	v_mfma_f32_16x16x32_bf16 v[108:111], v[188:191], v[222:225], v[108:111]
	v_mfma_f32_16x16x32_bf16 v[104:107], v[196:199], v[222:225], v[104:107]
	v_mfma_f32_16x16x32_bf16 v[92:95], v[188:191], v[230:233], v[92:95]
	v_mfma_f32_16x16x32_bf16 v[88:91], v[196:199], v[230:233], v[88:91]
	v_mfma_f32_16x16x32_bf16 v[76:79], v[188:191], v[238:241], v[76:79]
	v_mfma_f32_16x16x32_bf16 v[72:75], v[196:199], v[238:241], v[72:75]
	v_mfma_f32_16x16x32_bf16 v[124:127], v[192:195], v[218:221], v[124:127]
	v_mfma_f32_16x16x32_bf16 v[120:123], v[200:203], v[218:221], v[120:123]
	v_mfma_f32_16x16x32_bf16 v[108:111], v[192:195], v[226:229], v[108:111]
	v_mfma_f32_16x16x32_bf16 v[104:107], v[200:203], v[226:229], v[104:107]
	v_mfma_f32_16x16x32_bf16 v[92:95], v[192:195], v[234:237], v[92:95]
	v_mfma_f32_16x16x32_bf16 v[88:91], v[200:203], v[234:237], v[88:91]
	v_mfma_f32_16x16x32_bf16 v[76:79], v[192:195], v[242:245], v[76:79]
	v_mfma_f32_16x16x32_bf16 v[72:75], v[200:203], v[242:245], v[72:75]
	s_setprio 0
	s_barrier
	s_add_i32 s42, s45, s53
	s_mov_b32 m0, s42
	ds_read_b128 v[214:217], v173 offset:49152
	ds_read_b128 v[218:221], v173 offset:50176
	ds_read_b128 v[222:225], v173 offset:51200
	ds_read_b128 v[226:229], v173 offset:52224
	ds_read_b128 v[230:233], v173 offset:53248
	ds_read_b128 v[234:237], v173 offset:54272
	ds_read_b128 v[238:241], v173 offset:55296
	ds_read_b128 v[242:245], v173 offset:56320
	global_load_lds_dwordx4 v136, s[98:99]
	s_add_i32 m0, s42, 0x2000
	s_add_u32 s38, s38, 0x80080
	s_addc_u32 s39, s39, 0
	s_add_i32 s42, s47, s53
	global_load_lds_dwordx4 v140, s[98:99]
	s_mov_b32 m0, s42
	s_nop 0
	global_load_lds_dwordx4 v136, s[38:39]
	s_add_i32 m0, s42, 0x2000
	s_nop 0
	global_load_lds_dwordx4 v140, s[38:39]
	s_mov_b32 m0, s61
	s_nop 0
	global_load_lds_dwordx4 v14, s[100:101]
	s_mov_b32 m0, s64
	s_nop 0
	global_load_lds_dwordx4 v138, s[100:101]
	s_waitcnt vmcnt(8)
	s_waitcnt lgkmcnt(0)
	s_barrier
	s_setprio 1
	s_waitcnt lgkmcnt(0)
	v_mfma_f32_16x16x32_bf16 v[68:71], v[160:163], v[214:217], v[68:71]
	v_mfma_f32_16x16x32_bf16 v[64:67], v[174:177], v[214:217], v[64:67]
	v_mfma_f32_16x16x32_bf16 v[52:55], v[160:163], v[222:225], v[52:55]
	v_mfma_f32_16x16x32_bf16 v[48:51], v[174:177], v[222:225], v[48:51]
	v_mfma_f32_16x16x32_bf16 v[36:39], v[160:163], v[230:233], v[36:39]
	v_mfma_f32_16x16x32_bf16 v[30:33], v[174:177], v[230:233], v[30:33]
	v_mfma_f32_16x16x32_bf16 v[18:21], v[160:163], v[238:241], v[18:21]
	v_mfma_f32_16x16x32_bf16 v[10:13], v[174:177], v[238:241], v[10:13]
	v_mfma_f32_16x16x32_bf16 v[68:71], v[164:167], v[218:221], v[68:71]
	v_mfma_f32_16x16x32_bf16 v[64:67], v[184:187], v[218:221], v[64:67]
	v_mfma_f32_16x16x32_bf16 v[52:55], v[164:167], v[226:229], v[52:55]
	v_mfma_f32_16x16x32_bf16 v[48:51], v[184:187], v[226:229], v[48:51]
	v_mfma_f32_16x16x32_bf16 v[36:39], v[164:167], v[234:237], v[36:39]
	v_mfma_f32_16x16x32_bf16 v[30:33], v[184:187], v[234:237], v[30:33]
	v_mfma_f32_16x16x32_bf16 v[18:21], v[164:167], v[242:245], v[18:21]
	v_mfma_f32_16x16x32_bf16 v[10:13], v[184:187], v[242:245], v[10:13]
	s_setprio 0
	s_setprio 1
	v_mfma_f32_16x16x32_bf16 v[60:63], v[188:191], v[214:217], v[60:63]
	v_mfma_f32_16x16x32_bf16 v[56:59], v[196:199], v[214:217], v[56:59]
	v_mfma_f32_16x16x32_bf16 v[44:47], v[188:191], v[222:225], v[44:47]
	v_mfma_f32_16x16x32_bf16 v[40:43], v[196:199], v[222:225], v[40:43]
	v_mfma_f32_16x16x32_bf16 v[26:29], v[188:191], v[230:233], v[26:29]
	v_mfma_f32_16x16x32_bf16 v[22:25], v[196:199], v[230:233], v[22:25]
	v_mfma_f32_16x16x32_bf16 v[6:9], v[188:191], v[238:241], v[6:9]
	v_mfma_f32_16x16x32_bf16 v[2:5], v[196:199], v[238:241], v[2:5]
	v_mfma_f32_16x16x32_bf16 v[60:63], v[192:195], v[218:221], v[60:63]
	v_mfma_f32_16x16x32_bf16 v[56:59], v[200:203], v[218:221], v[56:59]
	v_mfma_f32_16x16x32_bf16 v[44:47], v[192:195], v[226:229], v[44:47]
	v_mfma_f32_16x16x32_bf16 v[40:43], v[200:203], v[226:229], v[40:43]
	v_mfma_f32_16x16x32_bf16 v[26:29], v[192:195], v[234:237], v[26:29]
	v_mfma_f32_16x16x32_bf16 v[22:25], v[200:203], v[234:237], v[22:25]
	v_mfma_f32_16x16x32_bf16 v[6:9], v[192:195], v[242:245], v[6:9]
	v_mfma_f32_16x16x32_bf16 v[2:5], v[200:203], v[242:245], v[2:5]
	s_setprio 0
	s_barrier
	s_add_i32 s27, s27, 2
	s_add_u32 s36, s36, 0x100
	s_addc_u32 s37, s37, 0
	s_add_u32 s25, s25, 0x100
	s_addc_u32 s26, s26, 0
	s_cmp_gt_u32 s27, 29
	s_cbranch_scc0 .LBB0_306
	s_and_b64 vcc, exec, s[28:29]
	s_cbranch_vccz .LBB0_309
	s_barrier

.LBB0_1124:
	s_add_i32 vcc_lo, s44, 2
	s_add_u32 s38, s8, 0x100
	s_addc_u32 s39, s9, 0
	s_add_i32 s72, 0, 0x10000
	s_cmp_eq_u32 s29, s44
	s_cselect_b32 s47, s35, s39
	s_cselect_b32 s46, s34, s38
	v_add_u32_e32 v34, s72, v183
	s_cselect_b32 s45, s49, s71
	s_cselect_b32 s44, s48, s70
	s_add_i32 s73, 0, 0x14000
	s_add_i32 m0, s25, 0xc000
	s_nop 0
	global_load_lds_dwordx4 v192, s[8:9]
	s_add_i32 m0, s25, 0xe000
	s_nop 0
	global_load_lds_dwordx4 v194, s[8:9]
	ds_read_b128 v[42:45], v34
	ds_read_b128 v[46:49], v34 offset:1024
	ds_read_b128 v[74:77], v34 offset:2048
	ds_read_b128 v[78:81], v34 offset:3072
	v_add_u32_e32 v34, s73, v183
	ds_read_b128 v[106:109], v34
	ds_read_b128 v[110:113], v34 offset:1024
	ds_read_b128 v[138:141], v34 offset:2048
	ds_read_b128 v[142:145], v34 offset:3072
	ds_read_b128 v[170:173], v205
	ds_read_b128 v[174:177], v205 offset:1024
	ds_read_b128 v[196:199], v205 offset:2048
	ds_read_b128 v[200:203], v205 offset:3072
	ds_read_b128 v[214:217], v205 offset:4096
	ds_read_b128 v[218:221], v205 offset:5120
	ds_read_b128 v[222:225], v205 offset:6144
	ds_read_b128 v[226:229], v205 offset:7168
	s_waitcnt vmcnt(8)
	s_waitcnt lgkmcnt(0)
	s_barrier
	s_setprio 1
	s_waitcnt lgkmcnt(0)
	v_mfma_f32_16x16x32_bf16 v[62:65], v[42:45], v[170:173], v[62:65]
	v_mfma_f32_16x16x32_bf16 v[58:61], v[74:77], v[170:173], v[58:61]
	v_mfma_f32_16x16x32_bf16 v[94:97], v[42:45], v[196:199], v[94:97]
	v_mfma_f32_16x16x32_bf16 v[90:93], v[74:77], v[196:199], v[90:93]
	v_mfma_f32_16x16x32_bf16 v[118:121], v[42:45], v[214:217], v[118:121]
	v_mfma_f32_16x16x32_bf16 v[114:117], v[74:77], v[214:217], v[114:117]
	v_mfma_f32_16x16x32_bf16 v[134:137], v[42:45], v[222:225], v[134:137]
	v_mfma_f32_16x16x32_bf16 v[130:133], v[74:77], v[222:225], v[130:133]
	v_mfma_f32_16x16x32_bf16 v[62:65], v[46:49], v[174:177], v[62:65]
	v_mfma_f32_16x16x32_bf16 v[58:61], v[78:81], v[174:177], v[58:61]
	v_mfma_f32_16x16x32_bf16 v[94:97], v[46:49], v[200:203], v[94:97]
	v_mfma_f32_16x16x32_bf16 v[90:93], v[78:81], v[200:203], v[90:93]
	v_mfma_f32_16x16x32_bf16 v[118:121], v[46:49], v[218:221], v[118:121]
	v_mfma_f32_16x16x32_bf16 v[114:117], v[78:81], v[218:221], v[114:117]
	v_mfma_f32_16x16x32_bf16 v[134:137], v[46:49], v[226:229], v[134:137]
	v_mfma_f32_16x16x32_bf16 v[130:133], v[78:81], v[226:229], v[130:133]
	s_setprio 0
	s_setprio 1
	v_mfma_f32_16x16x32_bf16 v[166:169], v[106:109], v[170:173], v[166:169]
	v_mfma_f32_16x16x32_bf16 v[162:165], v[138:141], v[170:173], v[162:165]
	v_mfma_f32_16x16x32_bf16 v[158:161], v[106:109], v[196:199], v[158:161]
	v_mfma_f32_16x16x32_bf16 v[154:157], v[138:141], v[196:199], v[154:157]
	v_mfma_f32_16x16x32_bf16 v[150:153], v[106:109], v[214:217], v[150:153]
	v_mfma_f32_16x16x32_bf16 v[146:149], v[138:141], v[214:217], v[146:149]
	v_mfma_f32_16x16x32_bf16 v[126:129], v[106:109], v[222:225], v[126:129]
	v_mfma_f32_16x16x32_bf16 v[122:125], v[138:141], v[222:225], v[122:125]
	v_mfma_f32_16x16x32_bf16 v[166:169], v[110:113], v[174:177], v[166:169]
	v_mfma_f32_16x16x32_bf16 v[162:165], v[142:145], v[174:177], v[162:165]
	v_mfma_f32_16x16x32_bf16 v[158:161], v[110:113], v[200:203], v[158:161]
	v_mfma_f32_16x16x32_bf16 v[154:157], v[142:145], v[200:203], v[154:157]
	v_mfma_f32_16x16x32_bf16 v[150:153], v[110:113], v[218:221], v[150:153]
	v_mfma_f32_16x16x32_bf16 v[146:149], v[142:145], v[218:221], v[146:149]
	v_mfma_f32_16x16x32_bf16 v[126:129], v[110:113], v[226:229], v[126:129]
	v_mfma_f32_16x16x32_bf16 v[122:125], v[142:145], v[226:229], v[122:125]
	s_setprio 0
	s_barrier
	s_add_u32 s98, s44, s22
	s_addc_u32 s99, s45, s23
	s_add_u32 s100, s46, s22
	s_addc_u32 s101, s47, s23
	s_add_i32 s8, s72, s20
	s_mov_b32 m0, s8
	ds_read_b128 v[170:173], v205 offset:16384
	ds_read_b128 v[174:177], v205 offset:17408
	ds_read_b128 v[196:199], v205 offset:18432
	ds_read_b128 v[200:203], v205 offset:19456
	ds_read_b128 v[214:217], v205 offset:20480
	ds_read_b128 v[218:221], v205 offset:21504
	ds_read_b128 v[222:225], v205 offset:22528
	ds_read_b128 v[226:229], v205 offset:23552
	global_load_lds_dwordx4 v184, s[44:45]
	s_add_i32 m0, s8, 0x2000
	s_add_u32 s8, s44, 0xc0000
	s_addc_u32 s9, s45, 0
	s_add_i32 s72, s73, s20
	global_load_lds_dwordx4 v188, s[44:45]
	s_mov_b32 m0, s72
	s_nop 0
	global_load_lds_dwordx4 v184, s[8:9]
	s_add_i32 m0, s72, 0x2000
	s_nop 0
	global_load_lds_dwordx4 v188, s[8:9]
	s_mov_b32 m0, s25
	s_nop 0
	global_load_lds_dwordx4 v14, s[46:47]
	s_mov_b32 m0, s26
	s_nop 0
	global_load_lds_dwordx4 v186, s[46:47]
	s_waitcnt vmcnt(8)
	s_waitcnt lgkmcnt(0)
	s_barrier
	s_setprio 1
	s_waitcnt lgkmcnt(0)
	v_mfma_f32_16x16x32_bf16 v[102:105], v[42:45], v[170:173], v[102:105]
	v_mfma_f32_16x16x32_bf16 v[98:101], v[74:77], v[170:173], v[98:101]
	v_mfma_f32_16x16x32_bf16 v[70:73], v[42:45], v[196:199], v[70:73]
	v_mfma_f32_16x16x32_bf16 v[66:69], v[74:77], v[196:199], v[66:69]
	v_mfma_f32_16x16x32_bf16 v[36:39], v[42:45], v[214:217], v[38:41]
	v_mfma_f32_16x16x32_bf16 v[30:33], v[74:77], v[214:217], v[30:33]
	v_mfma_f32_16x16x32_bf16 v[18:21], v[42:45], v[222:225], v[18:21]
	v_mfma_f32_16x16x32_bf16 v[10:13], v[74:77], v[222:225], v[10:13]
	v_mfma_f32_16x16x32_bf16 v[102:105], v[46:49], v[174:177], v[102:105]
	v_mfma_f32_16x16x32_bf16 v[98:101], v[78:81], v[174:177], v[98:101]
	v_mfma_f32_16x16x32_bf16 v[70:73], v[46:49], v[200:203], v[70:73]
	v_mfma_f32_16x16x32_bf16 v[66:69], v[78:81], v[200:203], v[66:69]
	v_mfma_f32_16x16x32_bf16 v[36:39], v[46:49], v[218:221], v[36:39]
	v_mfma_f32_16x16x32_bf16 v[30:33], v[78:81], v[218:221], v[30:33]
	v_mfma_f32_16x16x32_bf16 v[18:21], v[46:49], v[226:229], v[18:21]
	v_mfma_f32_16x16x32_bf16 v[10:13], v[78:81], v[226:229], v[10:13]
	s_setprio 0
	s_setprio 1
	v_mfma_f32_16x16x32_bf16 v[54:57], v[106:109], v[196:199], v[54:57]
	v_mfma_f32_16x16x32_bf16 v[50:53], v[138:141], v[196:199], v[50:53]
	v_mfma_f32_16x16x32_bf16 v[26:29], v[106:109], v[214:217], v[26:29]
	v_mfma_f32_16x16x32_bf16 v[22:25], v[138:141], v[214:217], v[22:25]
	v_mfma_f32_16x16x32_bf16 v[6:9], v[106:109], v[222:225], v[6:9]
	v_mfma_f32_16x16x32_bf16 v[2:5], v[138:141], v[222:225], v[2:5]
	v_mfma_f32_16x16x32_bf16 v[40:43], v[106:109], v[170:173], v[86:89]
	v_mfma_f32_16x16x32_bf16 v[46:49], v[138:141], v[170:173], v[82:85]
	v_mfma_f32_16x16x32_bf16 v[54:57], v[110:113], v[200:203], v[54:57]
	v_mfma_f32_16x16x32_bf16 v[50:53], v[142:145], v[200:203], v[50:53]
	v_mfma_f32_16x16x32_bf16 v[26:29], v[110:113], v[218:221], v[26:29]
	v_mfma_f32_16x16x32_bf16 v[22:25], v[142:145], v[218:221], v[22:25]
	v_mfma_f32_16x16x32_bf16 v[6:9], v[110:113], v[226:229], v[6:9]
	v_mfma_f32_16x16x32_bf16 v[2:5], v[142:145], v[226:229], v[2:5]
	v_mfma_f32_16x16x32_bf16 v[42:45], v[110:113], v[174:177], v[40:43]
	v_mfma_f32_16x16x32_bf16 v[46:49], v[142:145], v[174:177], v[46:49]
	s_setprio 0
	s_barrier
	s_add_i32 s72, 0, 0x18000
	v_add_u32_e32 v34, s72, v183
	s_add_i32 s73, 0, 0x1c000
	s_add_u32 s8, s46, 0xc0000
	s_addc_u32 s9, s47, 0
	s_mov_b32 m0, s27
	s_nop 0
	global_load_lds_dwordx4 v14, s[8:9]
	s_mov_b32 m0, s31
	s_nop 0
	global_load_lds_dwordx4 v186, s[8:9]
	ds_read_b128 v[74:77], v34
	ds_read_b128 v[78:81], v34 offset:1024
	ds_read_b128 v[82:85], v34 offset:2048
	ds_read_b128 v[86:89], v34 offset:3072
	v_add_u32_e32 v34, s73, v183
	ds_read_b128 v[106:109], v34
	ds_read_b128 v[110:113], v34 offset:1024
	ds_read_b128 v[138:141], v34 offset:2048
	ds_read_b128 v[142:145], v34 offset:3072
	ds_read_b128 v[170:173], v205 offset:32768
	ds_read_b128 v[174:177], v205 offset:33792
	ds_read_b128 v[196:199], v205 offset:34816
	ds_read_b128 v[200:203], v205 offset:35840
	ds_read_b128 v[214:217], v205 offset:36864
	ds_read_b128 v[218:221], v205 offset:37888
	ds_read_b128 v[222:225], v205 offset:38912
	ds_read_b128 v[226:229], v205 offset:39936
	s_waitcnt vmcnt(8)
	s_waitcnt lgkmcnt(0)
	s_barrier
	s_setprio 1
	s_waitcnt lgkmcnt(0)
	v_mfma_f32_16x16x32_bf16 v[62:65], v[74:77], v[170:173], v[62:65]
	v_mfma_f32_16x16x32_bf16 v[58:61], v[82:85], v[170:173], v[58:61]
	v_mfma_f32_16x16x32_bf16 v[94:97], v[74:77], v[196:199], v[94:97]
	v_mfma_f32_16x16x32_bf16 v[90:93], v[82:85], v[196:199], v[90:93]
	v_mfma_f32_16x16x32_bf16 v[118:121], v[74:77], v[214:217], v[118:121]
	v_mfma_f32_16x16x32_bf16 v[114:117], v[82:85], v[214:217], v[114:117]
	v_mfma_f32_16x16x32_bf16 v[134:137], v[74:77], v[222:225], v[134:137]
	v_mfma_f32_16x16x32_bf16 v[130:133], v[82:85], v[222:225], v[130:133]
	v_mfma_f32_16x16x32_bf16 v[62:65], v[78:81], v[174:177], v[62:65]
	v_mfma_f32_16x16x32_bf16 v[58:61], v[86:89], v[174:177], v[58:61]
	v_mfma_f32_16x16x32_bf16 v[94:97], v[78:81], v[200:203], v[94:97]
	v_mfma_f32_16x16x32_bf16 v[90:93], v[86:89], v[200:203], v[90:93]
	v_mfma_f32_16x16x32_bf16 v[118:121], v[78:81], v[218:221], v[118:121]
	v_mfma_f32_16x16x32_bf16 v[114:117], v[86:89], v[218:221], v[114:117]
	v_mfma_f32_16x16x32_bf16 v[134:137], v[78:81], v[226:229], v[134:137]
	v_mfma_f32_16x16x32_bf16 v[130:133], v[86:89], v[226:229], v[130:133]
	s_setprio 0
	s_setprio 1
	v_mfma_f32_16x16x32_bf16 v[166:169], v[106:109], v[170:173], v[166:169]
	v_mfma_f32_16x16x32_bf16 v[162:165], v[138:141], v[170:173], v[162:165]
	v_mfma_f32_16x16x32_bf16 v[158:161], v[106:109], v[196:199], v[158:161]
	v_mfma_f32_16x16x32_bf16 v[154:157], v[138:141], v[196:199], v[154:157]
	v_mfma_f32_16x16x32_bf16 v[150:153], v[106:109], v[214:217], v[150:153]
	v_mfma_f32_16x16x32_bf16 v[146:149], v[138:141], v[214:217], v[146:149]
	v_mfma_f32_16x16x32_bf16 v[126:129], v[106:109], v[222:225], v[126:129]
	v_mfma_f32_16x16x32_bf16 v[122:125], v[138:141], v[222:225], v[122:125]
	v_mfma_f32_16x16x32_bf16 v[166:169], v[110:113], v[174:177], v[166:169]
	v_mfma_f32_16x16x32_bf16 v[162:165], v[142:145], v[174:177], v[162:165]
	v_mfma_f32_16x16x32_bf16 v[158:161], v[110:113], v[200:203], v[158:161]
	v_mfma_f32_16x16x32_bf16 v[154:157], v[142:145], v[200:203], v[154:157]
	v_mfma_f32_16x16x32_bf16 v[150:153], v[110:113], v[218:221], v[150:153]
	v_mfma_f32_16x16x32_bf16 v[146:149], v[142:145], v[218:221], v[146:149]
	v_mfma_f32_16x16x32_bf16 v[126:129], v[110:113], v[226:229], v[126:129]
	v_mfma_f32_16x16x32_bf16 v[122:125], v[142:145], v[226:229], v[122:125]
	s_setprio 0
	s_barrier
	s_add_i32 s8, s72, s20
	s_mov_b32 m0, s8
	ds_read_b128 v[170:173], v205 offset:49152
	ds_read_b128 v[174:177], v205 offset:50176
	ds_read_b128 v[196:199], v205 offset:51200
	ds_read_b128 v[200:203], v205 offset:52224
	ds_read_b128 v[214:217], v205 offset:53248
	ds_read_b128 v[218:221], v205 offset:54272
	ds_read_b128 v[222:225], v205 offset:55296
	ds_read_b128 v[226:229], v205 offset:56320
	global_load_lds_dwordx4 v184, s[98:99]
	s_add_i32 m0, s8, 0x2000
	s_add_u32 s8, s44, 0xc0080
	s_addc_u32 s9, s45, 0
	s_add_i32 s44, s73, s20
	global_load_lds_dwordx4 v188, s[98:99]
	s_mov_b32 m0, s44
	s_nop 0
	global_load_lds_dwordx4 v184, s[8:9]
	s_add_i32 m0, s44, 0x2000
	s_nop 0
	global_load_lds_dwordx4 v188, s[8:9]
	s_mov_b32 m0, s52
	s_nop 0
	global_load_lds_dwordx4 v14, s[100:101]
	s_mov_b32 m0, s53
	s_nop 0
	global_load_lds_dwordx4 v186, s[100:101]
	s_waitcnt vmcnt(8)
	s_waitcnt lgkmcnt(0)
	s_barrier
	s_setprio 1
	s_waitcnt lgkmcnt(0)
	v_mfma_f32_16x16x32_bf16 v[102:105], v[74:77], v[170:173], v[102:105]
	v_mfma_f32_16x16x32_bf16 v[98:101], v[82:85], v[170:173], v[98:101]
	v_mfma_f32_16x16x32_bf16 v[70:73], v[74:77], v[196:199], v[70:73]
	v_mfma_f32_16x16x32_bf16 v[66:69], v[82:85], v[196:199], v[66:69]
	v_mfma_f32_16x16x32_bf16 v[36:39], v[74:77], v[214:217], v[36:39]
	v_mfma_f32_16x16x32_bf16 v[30:33], v[82:85], v[214:217], v[30:33]
	v_mfma_f32_16x16x32_bf16 v[18:21], v[74:77], v[222:225], v[18:21]
	v_mfma_f32_16x16x32_bf16 v[10:13], v[82:85], v[222:225], v[10:13]
	v_mfma_f32_16x16x32_bf16 v[102:105], v[78:81], v[174:177], v[102:105]
	v_mfma_f32_16x16x32_bf16 v[98:101], v[86:89], v[174:177], v[98:101]
	v_mfma_f32_16x16x32_bf16 v[70:73], v[78:81], v[200:203], v[70:73]
	v_mfma_f32_16x16x32_bf16 v[66:69], v[86:89], v[200:203], v[66:69]
	v_mfma_f32_16x16x32_bf16 v[38:41], v[78:81], v[218:221], v[36:39]
	v_mfma_f32_16x16x32_bf16 v[30:33], v[86:89], v[218:221], v[30:33]
	v_mfma_f32_16x16x32_bf16 v[18:21], v[78:81], v[226:229], v[18:21]
	v_mfma_f32_16x16x32_bf16 v[10:13], v[86:89], v[226:229], v[10:13]
	s_setprio 0
	s_setprio 1
	v_mfma_f32_16x16x32_bf16 v[42:45], v[106:109], v[170:173], v[42:45]
	v_mfma_f32_16x16x32_bf16 v[86:89], v[110:113], v[174:177], v[42:45]
	v_mfma_f32_16x16x32_bf16 v[42:45], v[138:141], v[170:173], v[46:49]
	v_mfma_f32_16x16x32_bf16 v[82:85], v[142:145], v[174:177], v[42:45]
	v_mfma_f32_16x16x32_bf16 v[42:45], v[106:109], v[196:199], v[54:57]
	v_mfma_f32_16x16x32_bf16 v[54:57], v[110:113], v[200:203], v[42:45]
	v_mfma_f32_16x16x32_bf16 v[42:45], v[138:141], v[196:199], v[50:53]
	v_mfma_f32_16x16x32_bf16 v[26:29], v[106:109], v[214:217], v[26:29]
	v_mfma_f32_16x16x32_bf16 v[22:25], v[138:141], v[214:217], v[22:25]
	v_mfma_f32_16x16x32_bf16 v[6:9], v[106:109], v[222:225], v[6:9]
	v_mfma_f32_16x16x32_bf16 v[2:5], v[138:141], v[222:225], v[2:5]
	v_mfma_f32_16x16x32_bf16 v[50:53], v[142:145], v[200:203], v[42:45]
	v_mfma_f32_16x16x32_bf16 v[26:29], v[110:113], v[218:221], v[26:29]
	v_mfma_f32_16x16x32_bf16 v[22:25], v[142:145], v[218:221], v[22:25]
	v_mfma_f32_16x16x32_bf16 v[6:9], v[110:113], v[226:229], v[6:9]
	v_mfma_f32_16x16x32_bf16 v[2:5], v[142:145], v[226:229], v[2:5]
	s_setprio 0
	s_barrier
	s_add_u32 s70, s70, 0x100
	s_addc_u32 s71, s71, 0
	s_cmp_ge_i32 vcc_lo, s51
	s_mov_b64 s[8:9], s[38:39]
	s_mov_b32 s44, vcc_lo
	s_cbranch_scc0 .LBB0_1124
	s_and_b64 vcc, exec, s[12:13]
	s_cbranch_vccz .LBB0_1127
	s_barrier

.LBB0_1508:
	s_add_i32 s39, s35, 2
	s_add_u32 s50, s48, 0xfff80080
	s_addc_u32 s51, s49, -1
	s_add_i32 s72, 0, 0x10000
	s_cmp_eq_u32 s9, s35
	s_cselect_b32 s53, s37, s51
	s_cselect_b32 s52, s36, s50
	s_cselect_b32 s51, s45, s29
	s_cselect_b32 s50, s44, s13
	s_add_i32 s35, 0, 0x14000
	v_add_u32_e32 v160, s72, v152
	v_add_u32_e32 v176, s35, v152
	s_add_i32 m0, s25, 0xc000
	s_nop 0
	global_load_lds_dwordx4 v144, s[48:49]
	s_add_i32 m0, s25, 0xe000
	s_nop 0
	global_load_lds_dwordx4 v146, s[48:49]
	ds_read_b128 v[136:139], v160
	ds_read_b128 v[148:151], v160 offset:1024
	ds_read_b128 v[156:159], v160 offset:2048
	ds_read_b128 v[160:163], v160 offset:3072
	ds_read_b128 v[164:167], v176
	ds_read_b128 v[168:171], v176 offset:1024
	ds_read_b128 v[172:175], v176 offset:2048
	ds_read_b128 v[184:187], v176 offset:3072
	ds_read_b128 v[188:191], v155
	ds_read_b128 v[192:195], v155 offset:1024
	ds_read_b128 v[196:199], v155 offset:2048
	ds_read_b128 v[200:203], v155 offset:3072
	ds_read_b128 v[214:217], v155 offset:4096
	ds_read_b128 v[218:221], v155 offset:5120
	ds_read_b128 v[222:225], v155 offset:6144
	ds_read_b128 v[226:229], v155 offset:7168
	s_waitcnt vmcnt(8)
	s_waitcnt lgkmcnt(0)
	s_barrier
	s_setprio 1
	s_waitcnt lgkmcnt(0)
	v_mfma_f32_16x16x32_bf16 v[132:135], v[136:139], v[188:191], v[132:135]
	v_mfma_f32_16x16x32_bf16 v[128:131], v[156:159], v[188:191], v[128:131]
	v_mfma_f32_16x16x32_bf16 v[116:119], v[136:139], v[196:199], v[116:119]
	v_mfma_f32_16x16x32_bf16 v[112:115], v[156:159], v[196:199], v[112:115]
	v_mfma_f32_16x16x32_bf16 v[100:103], v[136:139], v[214:217], v[100:103]
	v_mfma_f32_16x16x32_bf16 v[96:99], v[156:159], v[214:217], v[96:99]
	v_mfma_f32_16x16x32_bf16 v[84:87], v[136:139], v[222:225], v[84:87]
	v_mfma_f32_16x16x32_bf16 v[80:83], v[156:159], v[222:225], v[80:83]
	v_mfma_f32_16x16x32_bf16 v[132:135], v[148:151], v[192:195], v[132:135]
	v_mfma_f32_16x16x32_bf16 v[128:131], v[160:163], v[192:195], v[128:131]
	v_mfma_f32_16x16x32_bf16 v[116:119], v[148:151], v[200:203], v[116:119]
	v_mfma_f32_16x16x32_bf16 v[112:115], v[160:163], v[200:203], v[112:115]
	v_mfma_f32_16x16x32_bf16 v[100:103], v[148:151], v[218:221], v[100:103]
	v_mfma_f32_16x16x32_bf16 v[96:99], v[160:163], v[218:221], v[96:99]
	v_mfma_f32_16x16x32_bf16 v[84:87], v[148:151], v[226:229], v[84:87]
	v_mfma_f32_16x16x32_bf16 v[80:83], v[160:163], v[226:229], v[80:83]
	s_setprio 0
	s_setprio 1
	v_mfma_f32_16x16x32_bf16 v[124:127], v[164:167], v[188:191], v[124:127]
	v_mfma_f32_16x16x32_bf16 v[120:123], v[172:175], v[188:191], v[120:123]
	v_mfma_f32_16x16x32_bf16 v[108:111], v[164:167], v[196:199], v[108:111]
	v_mfma_f32_16x16x32_bf16 v[104:107], v[172:175], v[196:199], v[104:107]
	v_mfma_f32_16x16x32_bf16 v[92:95], v[164:167], v[214:217], v[92:95]
	v_mfma_f32_16x16x32_bf16 v[88:91], v[172:175], v[214:217], v[88:91]
	v_mfma_f32_16x16x32_bf16 v[76:79], v[164:167], v[222:225], v[76:79]
	v_mfma_f32_16x16x32_bf16 v[72:75], v[172:175], v[222:225], v[72:75]
	v_mfma_f32_16x16x32_bf16 v[124:127], v[168:171], v[192:195], v[124:127]
	v_mfma_f32_16x16x32_bf16 v[120:123], v[184:187], v[192:195], v[120:123]
	v_mfma_f32_16x16x32_bf16 v[108:111], v[168:171], v[200:203], v[108:111]
	v_mfma_f32_16x16x32_bf16 v[104:107], v[184:187], v[200:203], v[104:107]
	v_mfma_f32_16x16x32_bf16 v[92:95], v[168:171], v[218:221], v[92:95]
	v_mfma_f32_16x16x32_bf16 v[88:91], v[184:187], v[218:221], v[88:91]
	v_mfma_f32_16x16x32_bf16 v[76:79], v[168:171], v[226:229], v[76:79]
	v_mfma_f32_16x16x32_bf16 v[72:75], v[184:187], v[226:229], v[72:75]
	s_setprio 0
	s_barrier
	s_add_u32 s98, s50, s22
	s_addc_u32 s99, s51, s23
	s_add_u32 s100, s52, s22
	s_addc_u32 s101, s53, s23
	s_add_i32 s72, s72, s20
	s_mov_b32 m0, s72
	ds_read_b128 v[188:191], v155 offset:16384
	ds_read_b128 v[192:195], v155 offset:17408
	ds_read_b128 v[196:199], v155 offset:18432
	ds_read_b128 v[200:203], v155 offset:19456
	ds_read_b128 v[214:217], v155 offset:20480
	ds_read_b128 v[218:221], v155 offset:21504
	ds_read_b128 v[222:225], v155 offset:22528
	ds_read_b128 v[226:229], v155 offset:23552
	global_load_lds_dwordx4 v34, s[50:51]
	s_add_i32 m0, s72, 0x2000
	s_add_u32 s72, s50, 0x80000
	s_addc_u32 s73, s51, 0
	s_add_i32 s35, s35, s20
	global_load_lds_dwordx4 v142, s[50:51]
	s_mov_b32 m0, s35
	s_nop 0
	global_load_lds_dwordx4 v34, s[72:73]
	s_add_i32 m0, s35, 0x2000
	s_nop 0
	global_load_lds_dwordx4 v142, s[72:73]
	s_mov_b32 m0, s25
	s_nop 0
	global_load_lds_dwordx4 v14, s[52:53]
	s_mov_b32 m0, s26
	s_nop 0
	global_load_lds_dwordx4 v140, s[52:53]
	s_waitcnt vmcnt(8)
	s_waitcnt lgkmcnt(0)
	s_barrier
	s_setprio 1
	s_waitcnt lgkmcnt(0)
	v_mfma_f32_16x16x32_bf16 v[68:71], v[136:139], v[188:191], v[68:71]
	v_mfma_f32_16x16x32_bf16 v[64:67], v[156:159], v[188:191], v[64:67]
	v_mfma_f32_16x16x32_bf16 v[52:55], v[136:139], v[196:199], v[52:55]
	v_mfma_f32_16x16x32_bf16 v[48:51], v[156:159], v[196:199], v[48:51]
	v_mfma_f32_16x16x32_bf16 v[36:39], v[136:139], v[214:217], v[36:39]
	v_mfma_f32_16x16x32_bf16 v[30:33], v[156:159], v[214:217], v[30:33]
	v_mfma_f32_16x16x32_bf16 v[18:21], v[136:139], v[222:225], v[18:21]
	v_mfma_f32_16x16x32_bf16 v[10:13], v[156:159], v[222:225], v[10:13]
	v_mfma_f32_16x16x32_bf16 v[68:71], v[148:151], v[192:195], v[68:71]
	v_mfma_f32_16x16x32_bf16 v[64:67], v[160:163], v[192:195], v[64:67]
	v_mfma_f32_16x16x32_bf16 v[52:55], v[148:151], v[200:203], v[52:55]
	v_mfma_f32_16x16x32_bf16 v[48:51], v[160:163], v[200:203], v[48:51]
	v_mfma_f32_16x16x32_bf16 v[36:39], v[148:151], v[218:221], v[36:39]
	v_mfma_f32_16x16x32_bf16 v[30:33], v[160:163], v[218:221], v[30:33]
	v_mfma_f32_16x16x32_bf16 v[18:21], v[148:151], v[226:229], v[18:21]
	v_mfma_f32_16x16x32_bf16 v[10:13], v[160:163], v[226:229], v[10:13]
	s_setprio 0
	s_setprio 1
	v_mfma_f32_16x16x32_bf16 v[60:63], v[164:167], v[188:191], v[60:63]
	v_mfma_f32_16x16x32_bf16 v[56:59], v[172:175], v[188:191], v[56:59]
	v_mfma_f32_16x16x32_bf16 v[44:47], v[164:167], v[196:199], v[44:47]
	v_mfma_f32_16x16x32_bf16 v[40:43], v[172:175], v[196:199], v[40:43]
	v_mfma_f32_16x16x32_bf16 v[26:29], v[164:167], v[214:217], v[26:29]
	v_mfma_f32_16x16x32_bf16 v[22:25], v[172:175], v[214:217], v[22:25]
	v_mfma_f32_16x16x32_bf16 v[6:9], v[164:167], v[222:225], v[6:9]
	v_mfma_f32_16x16x32_bf16 v[2:5], v[172:175], v[222:225], v[2:5]
	v_mfma_f32_16x16x32_bf16 v[60:63], v[168:171], v[192:195], v[60:63]
	v_mfma_f32_16x16x32_bf16 v[56:59], v[184:187], v[192:195], v[56:59]
	v_mfma_f32_16x16x32_bf16 v[44:47], v[168:171], v[200:203], v[44:47]
	v_mfma_f32_16x16x32_bf16 v[40:43], v[184:187], v[200:203], v[40:43]
	v_mfma_f32_16x16x32_bf16 v[26:29], v[168:171], v[218:221], v[26:29]
	v_mfma_f32_16x16x32_bf16 v[22:25], v[184:187], v[218:221], v[22:25]
	v_mfma_f32_16x16x32_bf16 v[6:9], v[168:171], v[226:229], v[6:9]
	v_mfma_f32_16x16x32_bf16 v[2:5], v[184:187], v[226:229], v[2:5]
	s_setprio 0
	s_barrier
	s_add_i32 s35, 0, 0x18000
	s_add_i32 s72, 0, 0x1c000
	v_add_u32_e32 v160, s35, v152
	v_add_u32_e32 v183, s72, v152
	s_add_u32 s52, s52, 0x80000
	s_addc_u32 s53, s53, 0
	s_mov_b32 m0, s27
	s_nop 0
	global_load_lds_dwordx4 v14, s[52:53]
	s_mov_b32 m0, s31
	s_nop 0
	global_load_lds_dwordx4 v140, s[52:53]
	ds_read_b128 v[136:139], v160
	ds_read_b128 v[148:151], v160 offset:1024
	ds_read_b128 v[156:159], v160 offset:2048
	ds_read_b128 v[160:163], v160 offset:3072
	ds_read_b128 v[164:167], v183
	ds_read_b128 v[168:171], v183 offset:1024
	ds_read_b128 v[172:175], v183 offset:2048
	ds_read_b128 v[184:187], v183 offset:3072
	ds_read_b128 v[188:191], v155 offset:32768
	ds_read_b128 v[192:195], v155 offset:33792
	ds_read_b128 v[196:199], v155 offset:34816
	ds_read_b128 v[200:203], v155 offset:35840
	ds_read_b128 v[214:217], v155 offset:36864
	ds_read_b128 v[218:221], v155 offset:37888
	ds_read_b128 v[222:225], v155 offset:38912
	ds_read_b128 v[226:229], v155 offset:39936
	s_waitcnt vmcnt(8)
	s_waitcnt lgkmcnt(0)
	s_barrier
	s_setprio 1
	s_waitcnt lgkmcnt(0)
	v_mfma_f32_16x16x32_bf16 v[132:135], v[136:139], v[188:191], v[132:135]
	v_mfma_f32_16x16x32_bf16 v[128:131], v[156:159], v[188:191], v[128:131]
	v_mfma_f32_16x16x32_bf16 v[116:119], v[136:139], v[196:199], v[116:119]
	v_mfma_f32_16x16x32_bf16 v[112:115], v[156:159], v[196:199], v[112:115]
	v_mfma_f32_16x16x32_bf16 v[100:103], v[136:139], v[214:217], v[100:103]
	v_mfma_f32_16x16x32_bf16 v[96:99], v[156:159], v[214:217], v[96:99]
	v_mfma_f32_16x16x32_bf16 v[84:87], v[136:139], v[222:225], v[84:87]
	v_mfma_f32_16x16x32_bf16 v[80:83], v[156:159], v[222:225], v[80:83]
	v_mfma_f32_16x16x32_bf16 v[132:135], v[148:151], v[192:195], v[132:135]
	v_mfma_f32_16x16x32_bf16 v[128:131], v[160:163], v[192:195], v[128:131]
	v_mfma_f32_16x16x32_bf16 v[116:119], v[148:151], v[200:203], v[116:119]
	v_mfma_f32_16x16x32_bf16 v[112:115], v[160:163], v[200:203], v[112:115]
	v_mfma_f32_16x16x32_bf16 v[100:103], v[148:151], v[218:221], v[100:103]
	v_mfma_f32_16x16x32_bf16 v[96:99], v[160:163], v[218:221], v[96:99]
	v_mfma_f32_16x16x32_bf16 v[84:87], v[148:151], v[226:229], v[84:87]
	v_mfma_f32_16x16x32_bf16 v[80:83], v[160:163], v[226:229], v[80:83]
	s_setprio 0
	s_setprio 1
	v_mfma_f32_16x16x32_bf16 v[124:127], v[164:167], v[188:191], v[124:127]
	v_mfma_f32_16x16x32_bf16 v[120:123], v[172:175], v[188:191], v[120:123]
	v_mfma_f32_16x16x32_bf16 v[108:111], v[164:167], v[196:199], v[108:111]
	v_mfma_f32_16x16x32_bf16 v[104:107], v[172:175], v[196:199], v[104:107]
	v_mfma_f32_16x16x32_bf16 v[92:95], v[164:167], v[214:217], v[92:95]
	v_mfma_f32_16x16x32_bf16 v[88:91], v[172:175], v[214:217], v[88:91]
	v_mfma_f32_16x16x32_bf16 v[76:79], v[164:167], v[222:225], v[76:79]
	v_mfma_f32_16x16x32_bf16 v[72:75], v[172:175], v[222:225], v[72:75]
	v_mfma_f32_16x16x32_bf16 v[124:127], v[168:171], v[192:195], v[124:127]
	v_mfma_f32_16x16x32_bf16 v[120:123], v[184:187], v[192:195], v[120:123]
	v_mfma_f32_16x16x32_bf16 v[108:111], v[168:171], v[200:203], v[108:111]
	v_mfma_f32_16x16x32_bf16 v[104:107], v[184:187], v[200:203], v[104:107]
	v_mfma_f32_16x16x32_bf16 v[92:95], v[168:171], v[218:221], v[92:95]
	v_mfma_f32_16x16x32_bf16 v[88:91], v[184:187], v[218:221], v[88:91]
	v_mfma_f32_16x16x32_bf16 v[76:79], v[168:171], v[226:229], v[76:79]
	v_mfma_f32_16x16x32_bf16 v[72:75], v[184:187], v[226:229], v[72:75]
	s_setprio 0
	s_barrier
	s_add_i32 s35, s35, s20
	s_mov_b32 m0, s35
	ds_read_b128 v[188:191], v155 offset:49152
	ds_read_b128 v[192:195], v155 offset:50176
	ds_read_b128 v[196:199], v155 offset:51200
	ds_read_b128 v[200:203], v155 offset:52224
	ds_read_b128 v[214:217], v155 offset:53248
	ds_read_b128 v[218:221], v155 offset:54272
	ds_read_b128 v[222:225], v155 offset:55296
	ds_read_b128 v[226:229], v155 offset:56320
	global_load_lds_dwordx4 v34, s[98:99]
	s_add_i32 m0, s35, 0x2000
	s_add_u32 s50, s50, 0x80080
	s_addc_u32 s51, s51, 0
	s_add_i32 s35, s72, s20
	global_load_lds_dwordx4 v142, s[98:99]
	s_mov_b32 m0, s35
	s_nop 0
	global_load_lds_dwordx4 v34, s[50:51]
	s_add_i32 m0, s35, 0x2000
	s_nop 0
	global_load_lds_dwordx4 v142, s[50:51]
	s_mov_b32 m0, s60
	s_nop 0
	global_load_lds_dwordx4 v14, s[100:101]
	s_mov_b32 m0, s61
	s_nop 0
	global_load_lds_dwordx4 v140, s[100:101]
	s_waitcnt vmcnt(8)
	s_waitcnt lgkmcnt(0)
	s_barrier
	s_setprio 1
	s_waitcnt lgkmcnt(0)
	v_mfma_f32_16x16x32_bf16 v[68:71], v[136:139], v[188:191], v[68:71]
	v_mfma_f32_16x16x32_bf16 v[64:67], v[156:159], v[188:191], v[64:67]
	v_mfma_f32_16x16x32_bf16 v[52:55], v[136:139], v[196:199], v[52:55]
	v_mfma_f32_16x16x32_bf16 v[48:51], v[156:159], v[196:199], v[48:51]
	v_mfma_f32_16x16x32_bf16 v[36:39], v[136:139], v[214:217], v[36:39]
	v_mfma_f32_16x16x32_bf16 v[30:33], v[156:159], v[214:217], v[30:33]
	v_mfma_f32_16x16x32_bf16 v[18:21], v[136:139], v[222:225], v[18:21]
	v_mfma_f32_16x16x32_bf16 v[10:13], v[156:159], v[222:225], v[10:13]
	v_mfma_f32_16x16x32_bf16 v[68:71], v[148:151], v[192:195], v[68:71]
	v_mfma_f32_16x16x32_bf16 v[64:67], v[160:163], v[192:195], v[64:67]
	v_mfma_f32_16x16x32_bf16 v[52:55], v[148:151], v[200:203], v[52:55]
	v_mfma_f32_16x16x32_bf16 v[48:51], v[160:163], v[200:203], v[48:51]
	v_mfma_f32_16x16x32_bf16 v[36:39], v[148:151], v[218:221], v[36:39]
	v_mfma_f32_16x16x32_bf16 v[30:33], v[160:163], v[218:221], v[30:33]
	v_mfma_f32_16x16x32_bf16 v[18:21], v[148:151], v[226:229], v[18:21]
	v_mfma_f32_16x16x32_bf16 v[10:13], v[160:163], v[226:229], v[10:13]
	s_setprio 0
	s_setprio 1
	v_mfma_f32_16x16x32_bf16 v[60:63], v[164:167], v[188:191], v[60:63]
	v_mfma_f32_16x16x32_bf16 v[56:59], v[172:175], v[188:191], v[56:59]
	v_mfma_f32_16x16x32_bf16 v[44:47], v[164:167], v[196:199], v[44:47]
	v_mfma_f32_16x16x32_bf16 v[40:43], v[172:175], v[196:199], v[40:43]
	v_mfma_f32_16x16x32_bf16 v[26:29], v[164:167], v[214:217], v[26:29]
	v_mfma_f32_16x16x32_bf16 v[22:25], v[172:175], v[214:217], v[22:25]
	v_mfma_f32_16x16x32_bf16 v[6:9], v[164:167], v[222:225], v[6:9]
	v_mfma_f32_16x16x32_bf16 v[2:5], v[172:175], v[222:225], v[2:5]
	v_mfma_f32_16x16x32_bf16 v[60:63], v[168:171], v[192:195], v[60:63]
	v_mfma_f32_16x16x32_bf16 v[56:59], v[184:187], v[192:195], v[56:59]
	v_mfma_f32_16x16x32_bf16 v[44:47], v[168:171], v[200:203], v[44:47]
	v_mfma_f32_16x16x32_bf16 v[40:43], v[184:187], v[200:203], v[40:43]
	v_mfma_f32_16x16x32_bf16 v[26:29], v[168:171], v[218:221], v[26:29]
	v_mfma_f32_16x16x32_bf16 v[22:25], v[184:187], v[218:221], v[22:25]
	v_mfma_f32_16x16x32_bf16 v[6:9], v[168:171], v[226:229], v[6:9]
	v_mfma_f32_16x16x32_bf16 v[2:5], v[184:187], v[226:229], v[2:5]
	s_setprio 0
	s_barrier
	s_add_u32 s48, s48, 0x100
	s_addc_u32 s49, s49, 0
	s_add_u32 s13, s13, 0x100
	s_addc_u32 s29, s29, 0
	s_cmp_ge_i32 s39, s71
	s_mov_b32 s35, s39
	s_cbranch_scc0 .LBB0_1508
	s_and_b64 vcc, exec, s[10:11]
	s_cbranch_vccz .LBB0_1511

.LBB0_1664:
	s_add_u32 s44, s42, 0xfff80080
	s_addc_u32 s45, s43, -1
	s_add_i32 s64, 0, 0x10000
	s_cmp_eq_u32 s61, 28
	s_cselect_b32 s47, s29, s45
	s_cselect_b32 s46, s53, s44
	v_add_u32_e32 v151, s64, v141
	s_cselect_b32 s45, s13, s60
	s_cselect_b32 s44, s54, s55
	s_add_i32 s67, 0, 0x14000
	s_add_i32 m0, s25, 0xc000
	s_nop 0
	global_load_lds_dwordx4 v142, s[42:43]
	s_add_i32 m0, s25, 0xe000
	s_nop 0
	global_load_lds_dwordx4 v144, s[42:43]
	ds_read_b128 v[162:165], v151
	ds_read_b128 v[166:169], v151 offset:1024
	ds_read_b128 v[170:173], v151 offset:2048
	ds_read_b128 v[174:177], v151 offset:3072
	v_add_u32_e32 v151, s67, v141
	ds_read_b128 v[184:187], v151
	ds_read_b128 v[188:191], v151 offset:1024
	ds_read_b128 v[192:195], v151 offset:2048
	ds_read_b128 v[196:199], v151 offset:3072
	ds_read_b128 v[200:203], v149
	ds_read_b128 v[214:217], v149 offset:1024
	ds_read_b128 v[218:221], v149 offset:2048
	ds_read_b128 v[222:225], v149 offset:3072
	ds_read_b128 v[226:229], v149 offset:4096
	ds_read_b128 v[230:233], v149 offset:5120
	ds_read_b128 v[234:237], v149 offset:6144
	ds_read_b128 v[238:241], v149 offset:7168
	s_waitcnt vmcnt(8)
	s_waitcnt lgkmcnt(0)
	s_barrier
	s_setprio 1
	s_waitcnt lgkmcnt(0)
	v_mfma_f32_16x16x32_bf16 v[132:135], v[162:165], v[200:203], v[132:135]
	v_mfma_f32_16x16x32_bf16 v[128:131], v[170:173], v[200:203], v[128:131]
	v_mfma_f32_16x16x32_bf16 v[116:119], v[162:165], v[218:221], v[116:119]
	v_mfma_f32_16x16x32_bf16 v[112:115], v[170:173], v[218:221], v[112:115]
	v_mfma_f32_16x16x32_bf16 v[100:103], v[162:165], v[226:229], v[100:103]
	v_mfma_f32_16x16x32_bf16 v[96:99], v[170:173], v[226:229], v[96:99]
	v_mfma_f32_16x16x32_bf16 v[84:87], v[162:165], v[234:237], v[84:87]
	v_mfma_f32_16x16x32_bf16 v[80:83], v[170:173], v[234:237], v[80:83]
	v_mfma_f32_16x16x32_bf16 v[132:135], v[166:169], v[214:217], v[132:135]
	v_mfma_f32_16x16x32_bf16 v[128:131], v[174:177], v[214:217], v[128:131]
	v_mfma_f32_16x16x32_bf16 v[116:119], v[166:169], v[222:225], v[116:119]
	v_mfma_f32_16x16x32_bf16 v[112:115], v[174:177], v[222:225], v[112:115]
	v_mfma_f32_16x16x32_bf16 v[100:103], v[166:169], v[230:233], v[100:103]
	v_mfma_f32_16x16x32_bf16 v[96:99], v[174:177], v[230:233], v[96:99]
	v_mfma_f32_16x16x32_bf16 v[84:87], v[166:169], v[238:241], v[84:87]
	v_mfma_f32_16x16x32_bf16 v[80:83], v[174:177], v[238:241], v[80:83]
	s_setprio 0
	s_setprio 1
	v_mfma_f32_16x16x32_bf16 v[124:127], v[184:187], v[200:203], v[124:127]
	v_mfma_f32_16x16x32_bf16 v[120:123], v[192:195], v[200:203], v[120:123]
	v_mfma_f32_16x16x32_bf16 v[108:111], v[184:187], v[218:221], v[108:111]
	v_mfma_f32_16x16x32_bf16 v[104:107], v[192:195], v[218:221], v[104:107]
	v_mfma_f32_16x16x32_bf16 v[92:95], v[184:187], v[226:229], v[92:95]
	v_mfma_f32_16x16x32_bf16 v[88:91], v[192:195], v[226:229], v[88:91]
	v_mfma_f32_16x16x32_bf16 v[76:79], v[184:187], v[234:237], v[76:79]
	v_mfma_f32_16x16x32_bf16 v[72:75], v[192:195], v[234:237], v[72:75]
	v_mfma_f32_16x16x32_bf16 v[124:127], v[188:191], v[214:217], v[124:127]
	v_mfma_f32_16x16x32_bf16 v[120:123], v[196:199], v[214:217], v[120:123]
	v_mfma_f32_16x16x32_bf16 v[108:111], v[188:191], v[222:225], v[108:111]
	v_mfma_f32_16x16x32_bf16 v[104:107], v[196:199], v[222:225], v[104:107]
	v_mfma_f32_16x16x32_bf16 v[92:95], v[188:191], v[230:233], v[92:95]
	v_mfma_f32_16x16x32_bf16 v[88:91], v[196:199], v[230:233], v[88:91]
	v_mfma_f32_16x16x32_bf16 v[76:79], v[188:191], v[238:241], v[76:79]
	v_mfma_f32_16x16x32_bf16 v[72:75], v[196:199], v[238:241], v[72:75]
	s_setprio 0
	s_barrier
	s_add_u32 s98, s44, s22
	s_addc_u32 s99, s45, s23
	s_add_u32 s100, s46, s22
	s_addc_u32 s101, s47, s23
	s_add_i32 s64, s64, s20
	s_mov_b32 m0, s64
	ds_read_b128 v[200:203], v149 offset:16384
	ds_read_b128 v[214:217], v149 offset:17408
	ds_read_b128 v[218:221], v149 offset:18432
	ds_read_b128 v[222:225], v149 offset:19456
	ds_read_b128 v[226:229], v149 offset:20480
	ds_read_b128 v[230:233], v149 offset:21504
	ds_read_b128 v[234:237], v149 offset:22528
	ds_read_b128 v[238:241], v149 offset:23552
	global_load_lds_dwordx4 v34, s[44:45]
	s_add_i32 m0, s64, 0x2000
	s_add_u32 s64, s44, 0x80000
	s_addc_u32 s65, s45, 0
	s_add_i32 s67, s67, s20
	global_load_lds_dwordx4 v14, s[44:45]
	s_mov_b32 m0, s67
	s_nop 0
	global_load_lds_dwordx4 v34, s[64:65]
	s_add_i32 m0, s67, 0x2000
	s_nop 0
	global_load_lds_dwordx4 v14, s[64:65]
	s_mov_b32 m0, s25
	s_nop 0
	global_load_lds_dwordx4 v138, s[46:47]
	s_mov_b32 m0, s26
	s_nop 0
	global_load_lds_dwordx4 v136, s[46:47]
	s_waitcnt vmcnt(8)
	s_waitcnt lgkmcnt(0)
	s_barrier
	s_setprio 1
	s_waitcnt lgkmcnt(0)
	v_mfma_f32_16x16x32_bf16 v[68:71], v[162:165], v[200:203], v[68:71]
	v_mfma_f32_16x16x32_bf16 v[64:67], v[170:173], v[200:203], v[64:67]
	v_mfma_f32_16x16x32_bf16 v[52:55], v[162:165], v[218:221], v[52:55]
	v_mfma_f32_16x16x32_bf16 v[48:51], v[170:173], v[218:221], v[48:51]
	v_mfma_f32_16x16x32_bf16 v[36:39], v[162:165], v[226:229], v[36:39]
	v_mfma_f32_16x16x32_bf16 v[30:33], v[170:173], v[226:229], v[30:33]
	v_mfma_f32_16x16x32_bf16 v[18:21], v[162:165], v[234:237], v[18:21]
	v_mfma_f32_16x16x32_bf16 v[10:13], v[170:173], v[234:237], v[10:13]
	v_mfma_f32_16x16x32_bf16 v[68:71], v[166:169], v[214:217], v[68:71]
	v_mfma_f32_16x16x32_bf16 v[64:67], v[174:177], v[214:217], v[64:67]
	v_mfma_f32_16x16x32_bf16 v[52:55], v[166:169], v[222:225], v[52:55]
	v_mfma_f32_16x16x32_bf16 v[48:51], v[174:177], v[222:225], v[48:51]
	v_mfma_f32_16x16x32_bf16 v[36:39], v[166:169], v[230:233], v[36:39]
	v_mfma_f32_16x16x32_bf16 v[30:33], v[174:177], v[230:233], v[30:33]
	v_mfma_f32_16x16x32_bf16 v[18:21], v[166:169], v[238:241], v[18:21]
	v_mfma_f32_16x16x32_bf16 v[10:13], v[174:177], v[238:241], v[10:13]
	s_setprio 0
	s_setprio 1
	v_mfma_f32_16x16x32_bf16 v[60:63], v[184:187], v[200:203], v[60:63]
	v_mfma_f32_16x16x32_bf16 v[56:59], v[192:195], v[200:203], v[56:59]
	v_mfma_f32_16x16x32_bf16 v[44:47], v[184:187], v[218:221], v[44:47]
	v_mfma_f32_16x16x32_bf16 v[40:43], v[192:195], v[218:221], v[40:43]
	v_mfma_f32_16x16x32_bf16 v[26:29], v[184:187], v[226:229], v[26:29]
	v_mfma_f32_16x16x32_bf16 v[22:25], v[192:195], v[226:229], v[22:25]
	v_mfma_f32_16x16x32_bf16 v[6:9], v[184:187], v[234:237], v[6:9]
	v_mfma_f32_16x16x32_bf16 v[2:5], v[192:195], v[234:237], v[2:5]
	v_mfma_f32_16x16x32_bf16 v[60:63], v[188:191], v[214:217], v[60:63]
	v_mfma_f32_16x16x32_bf16 v[56:59], v[196:199], v[214:217], v[56:59]
	v_mfma_f32_16x16x32_bf16 v[44:47], v[188:191], v[222:225], v[44:47]
	v_mfma_f32_16x16x32_bf16 v[40:43], v[196:199], v[222:225], v[40:43]
	v_mfma_f32_16x16x32_bf16 v[26:29], v[188:191], v[230:233], v[26:29]
	v_mfma_f32_16x16x32_bf16 v[22:25], v[196:199], v[230:233], v[22:25]
	v_mfma_f32_16x16x32_bf16 v[6:9], v[188:191], v[238:241], v[6:9]
	v_mfma_f32_16x16x32_bf16 v[2:5], v[196:199], v[238:241], v[2:5]
	s_setprio 0
	s_barrier
	s_add_i32 s64, 0, 0x18000
	v_add_u32_e32 v151, s64, v141
	s_add_i32 s65, 0, 0x1c000
	s_add_u32 s46, s46, 0x80000
	s_addc_u32 s47, s47, 0
	s_mov_b32 m0, s27
	s_nop 0
	global_load_lds_dwordx4 v138, s[46:47]
	s_mov_b32 m0, s31
	s_nop 0
	global_load_lds_dwordx4 v136, s[46:47]
	ds_read_b128 v[162:165], v151
	ds_read_b128 v[166:169], v151 offset:1024
	ds_read_b128 v[170:173], v151 offset:2048
	ds_read_b128 v[174:177], v151 offset:3072
	v_add_u32_e32 v151, s65, v141
	ds_read_b128 v[184:187], v151
	ds_read_b128 v[188:191], v151 offset:1024
	ds_read_b128 v[192:195], v151 offset:2048
	ds_read_b128 v[196:199], v151 offset:3072
	ds_read_b128 v[200:203], v149 offset:32768
	ds_read_b128 v[214:217], v149 offset:33792
	ds_read_b128 v[218:221], v149 offset:34816
	ds_read_b128 v[222:225], v149 offset:35840
	ds_read_b128 v[226:229], v149 offset:36864
	ds_read_b128 v[230:233], v149 offset:37888
	ds_read_b128 v[234:237], v149 offset:38912
	ds_read_b128 v[238:241], v149 offset:39936
	s_waitcnt vmcnt(8)
	s_waitcnt lgkmcnt(0)
	s_barrier
	s_setprio 1
	s_waitcnt lgkmcnt(0)
	v_mfma_f32_16x16x32_bf16 v[132:135], v[162:165], v[200:203], v[132:135]
	v_mfma_f32_16x16x32_bf16 v[128:131], v[170:173], v[200:203], v[128:131]
	v_mfma_f32_16x16x32_bf16 v[116:119], v[162:165], v[218:221], v[116:119]
	v_mfma_f32_16x16x32_bf16 v[112:115], v[170:173], v[218:221], v[112:115]
	v_mfma_f32_16x16x32_bf16 v[100:103], v[162:165], v[226:229], v[100:103]
	v_mfma_f32_16x16x32_bf16 v[96:99], v[170:173], v[226:229], v[96:99]
	v_mfma_f32_16x16x32_bf16 v[84:87], v[162:165], v[234:237], v[84:87]
	v_mfma_f32_16x16x32_bf16 v[80:83], v[170:173], v[234:237], v[80:83]
	v_mfma_f32_16x16x32_bf16 v[132:135], v[166:169], v[214:217], v[132:135]
	v_mfma_f32_16x16x32_bf16 v[128:131], v[174:177], v[214:217], v[128:131]
	v_mfma_f32_16x16x32_bf16 v[116:119], v[166:169], v[222:225], v[116:119]
	v_mfma_f32_16x16x32_bf16 v[112:115], v[174:177], v[222:225], v[112:115]
	v_mfma_f32_16x16x32_bf16 v[100:103], v[166:169], v[230:233], v[100:103]
	v_mfma_f32_16x16x32_bf16 v[96:99], v[174:177], v[230:233], v[96:99]
	v_mfma_f32_16x16x32_bf16 v[84:87], v[166:169], v[238:241], v[84:87]
	v_mfma_f32_16x16x32_bf16 v[80:83], v[174:177], v[238:241], v[80:83]
	s_setprio 0
	s_setprio 1
	v_mfma_f32_16x16x32_bf16 v[124:127], v[184:187], v[200:203], v[124:127]
	v_mfma_f32_16x16x32_bf16 v[120:123], v[192:195], v[200:203], v[120:123]
	v_mfma_f32_16x16x32_bf16 v[108:111], v[184:187], v[218:221], v[108:111]
	v_mfma_f32_16x16x32_bf16 v[104:107], v[192:195], v[218:221], v[104:107]
	v_mfma_f32_16x16x32_bf16 v[92:95], v[184:187], v[226:229], v[92:95]
	v_mfma_f32_16x16x32_bf16 v[88:91], v[192:195], v[226:229], v[88:91]
	v_mfma_f32_16x16x32_bf16 v[76:79], v[184:187], v[234:237], v[76:79]
	v_mfma_f32_16x16x32_bf16 v[72:75], v[192:195], v[234:237], v[72:75]
	v_mfma_f32_16x16x32_bf16 v[124:127], v[188:191], v[214:217], v[124:127]
	v_mfma_f32_16x16x32_bf16 v[120:123], v[196:199], v[214:217], v[120:123]
	v_mfma_f32_16x16x32_bf16 v[108:111], v[188:191], v[222:225], v[108:111]
	v_mfma_f32_16x16x32_bf16 v[104:107], v[196:199], v[222:225], v[104:107]
	v_mfma_f32_16x16x32_bf16 v[92:95], v[188:191], v[230:233], v[92:95]
	v_mfma_f32_16x16x32_bf16 v[88:91], v[196:199], v[230:233], v[88:91]
	v_mfma_f32_16x16x32_bf16 v[76:79], v[188:191], v[238:241], v[76:79]
	v_mfma_f32_16x16x32_bf16 v[72:75], v[196:199], v[238:241], v[72:75]
	s_setprio 0
	s_barrier
	s_add_i32 s46, s64, s20
	s_mov_b32 m0, s46
	ds_read_b128 v[200:203], v149 offset:49152
	ds_read_b128 v[214:217], v149 offset:50176
	ds_read_b128 v[218:221], v149 offset:51200
	ds_read_b128 v[222:225], v149 offset:52224
	ds_read_b128 v[226:229], v149 offset:53248
	ds_read_b128 v[230:233], v149 offset:54272
	ds_read_b128 v[234:237], v149 offset:55296
	ds_read_b128 v[238:241], v149 offset:56320
	global_load_lds_dwordx4 v34, s[98:99]
	s_add_i32 m0, s46, 0x2000
	s_add_u32 s44, s44, 0x80080
	s_addc_u32 s45, s45, 0
	s_add_i32 s46, s65, s20
	global_load_lds_dwordx4 v14, s[98:99]
	s_mov_b32 m0, s46
	s_nop 0
	global_load_lds_dwordx4 v34, s[44:45]
	s_add_i32 m0, s46, 0x2000
	s_nop 0
	global_load_lds_dwordx4 v14, s[44:45]
	s_mov_b32 m0, s48
	s_nop 0
	global_load_lds_dwordx4 v138, s[100:101]
	s_mov_b32 m0, s49
	s_nop 0
	global_load_lds_dwordx4 v136, s[100:101]
	s_waitcnt vmcnt(8)
	s_waitcnt lgkmcnt(0)
	s_barrier
	s_setprio 1
	s_waitcnt lgkmcnt(0)
	v_mfma_f32_16x16x32_bf16 v[68:71], v[162:165], v[200:203], v[68:71]
	v_mfma_f32_16x16x32_bf16 v[64:67], v[170:173], v[200:203], v[64:67]
	v_mfma_f32_16x16x32_bf16 v[52:55], v[162:165], v[218:221], v[52:55]
	v_mfma_f32_16x16x32_bf16 v[48:51], v[170:173], v[218:221], v[48:51]
	v_mfma_f32_16x16x32_bf16 v[36:39], v[162:165], v[226:229], v[36:39]
	v_mfma_f32_16x16x32_bf16 v[30:33], v[170:173], v[226:229], v[30:33]
	v_mfma_f32_16x16x32_bf16 v[18:21], v[162:165], v[234:237], v[18:21]
	v_mfma_f32_16x16x32_bf16 v[10:13], v[170:173], v[234:237], v[10:13]
	v_mfma_f32_16x16x32_bf16 v[68:71], v[166:169], v[214:217], v[68:71]
	v_mfma_f32_16x16x32_bf16 v[64:67], v[174:177], v[214:217], v[64:67]
	v_mfma_f32_16x16x32_bf16 v[52:55], v[166:169], v[222:225], v[52:55]
	v_mfma_f32_16x16x32_bf16 v[48:51], v[174:177], v[222:225], v[48:51]
	v_mfma_f32_16x16x32_bf16 v[36:39], v[166:169], v[230:233], v[36:39]
	v_mfma_f32_16x16x32_bf16 v[30:33], v[174:177], v[230:233], v[30:33]
	v_mfma_f32_16x16x32_bf16 v[18:21], v[166:169], v[238:241], v[18:21]
	v_mfma_f32_16x16x32_bf16 v[10:13], v[174:177], v[238:241], v[10:13]
	s_setprio 0
	s_setprio 1
	v_mfma_f32_16x16x32_bf16 v[60:63], v[184:187], v[200:203], v[60:63]
	v_mfma_f32_16x16x32_bf16 v[56:59], v[192:195], v[200:203], v[56:59]
	v_mfma_f32_16x16x32_bf16 v[44:47], v[184:187], v[218:221], v[44:47]
	v_mfma_f32_16x16x32_bf16 v[40:43], v[192:195], v[218:221], v[40:43]
	v_mfma_f32_16x16x32_bf16 v[26:29], v[184:187], v[226:229], v[26:29]
	v_mfma_f32_16x16x32_bf16 v[22:25], v[192:195], v[226:229], v[22:25]
	v_mfma_f32_16x16x32_bf16 v[6:9], v[184:187], v[234:237], v[6:9]
	v_mfma_f32_16x16x32_bf16 v[2:5], v[192:195], v[234:237], v[2:5]
	v_mfma_f32_16x16x32_bf16 v[60:63], v[188:191], v[214:217], v[60:63]
	v_mfma_f32_16x16x32_bf16 v[56:59], v[196:199], v[214:217], v[56:59]
	v_mfma_f32_16x16x32_bf16 v[44:47], v[188:191], v[222:225], v[44:47]
	v_mfma_f32_16x16x32_bf16 v[40:43], v[196:199], v[222:225], v[40:43]
	v_mfma_f32_16x16x32_bf16 v[26:29], v[188:191], v[230:233], v[26:29]
	v_mfma_f32_16x16x32_bf16 v[22:25], v[196:199], v[230:233], v[22:25]
	v_mfma_f32_16x16x32_bf16 v[6:9], v[188:191], v[238:241], v[6:9]
	v_mfma_f32_16x16x32_bf16 v[2:5], v[196:199], v[238:241], v[2:5]
	s_setprio 0
	s_barrier
	s_add_i32 s61, s61, 2
	s_add_u32 s42, s42, 0x100
	s_addc_u32 s43, s43, 0
	s_add_u32 s55, s55, 0x100
	s_addc_u32 s60, s60, 0
	s_cmp_gt_u32 s61, 29
	s_cbranch_scc0 .LBB0_1664
	s_and_b64 vcc, exec, s[10:11]
	s_cbranch_vccz .LBB0_1667
	s_barrier

.LBB0_1764:
	s_add_i32 vcc_lo, s44, 2
	s_add_u32 s42, s36, 0x100
	s_addc_u32 s43, s37, 0
	s_add_i32 s72, 0, 0x10000
	s_cmp_eq_u32 s11, s44
	s_cselect_b32 s47, s13, s43
	s_cselect_b32 s46, s12, s42
	s_cselect_b32 s45, s29, s71
	s_cselect_b32 s44, s28, s70
	s_add_i32 s73, 0, 0x14000
	v_add_u32_e32 v160, s72, v152
	v_add_u32_e32 v176, s73, v152
	s_add_i32 m0, s25, 0xc000
	s_nop 0
	global_load_lds_dwordx4 v144, s[36:37]
	s_add_i32 m0, s25, 0xe000
	s_nop 0
	global_load_lds_dwordx4 v146, s[36:37]
	ds_read_b128 v[136:139], v160
	ds_read_b128 v[148:151], v160 offset:1024
	ds_read_b128 v[156:159], v160 offset:2048
	ds_read_b128 v[160:163], v160 offset:3072
	ds_read_b128 v[164:167], v176
	ds_read_b128 v[168:171], v176 offset:1024
	ds_read_b128 v[172:175], v176 offset:2048
	ds_read_b128 v[184:187], v176 offset:3072
	ds_read_b128 v[188:191], v155
	ds_read_b128 v[192:195], v155 offset:1024
	ds_read_b128 v[196:199], v155 offset:2048
	ds_read_b128 v[200:203], v155 offset:3072
	ds_read_b128 v[214:217], v155 offset:4096
	ds_read_b128 v[218:221], v155 offset:5120
	ds_read_b128 v[222:225], v155 offset:6144
	ds_read_b128 v[226:229], v155 offset:7168
	s_waitcnt vmcnt(8)
	s_waitcnt lgkmcnt(0)
	s_barrier
	s_setprio 1
	s_waitcnt lgkmcnt(0)
	v_mfma_f32_16x16x32_bf16 v[132:135], v[136:139], v[188:191], v[132:135]
	v_mfma_f32_16x16x32_bf16 v[128:131], v[156:159], v[188:191], v[128:131]
	v_mfma_f32_16x16x32_bf16 v[116:119], v[136:139], v[196:199], v[116:119]
	v_mfma_f32_16x16x32_bf16 v[112:115], v[156:159], v[196:199], v[112:115]
	v_mfma_f32_16x16x32_bf16 v[100:103], v[136:139], v[214:217], v[100:103]
	v_mfma_f32_16x16x32_bf16 v[96:99], v[156:159], v[214:217], v[96:99]
	v_mfma_f32_16x16x32_bf16 v[84:87], v[136:139], v[222:225], v[84:87]
	v_mfma_f32_16x16x32_bf16 v[80:83], v[156:159], v[222:225], v[80:83]
	v_mfma_f32_16x16x32_bf16 v[132:135], v[148:151], v[192:195], v[132:135]
	v_mfma_f32_16x16x32_bf16 v[128:131], v[160:163], v[192:195], v[128:131]
	v_mfma_f32_16x16x32_bf16 v[116:119], v[148:151], v[200:203], v[116:119]
	v_mfma_f32_16x16x32_bf16 v[112:115], v[160:163], v[200:203], v[112:115]
	v_mfma_f32_16x16x32_bf16 v[100:103], v[148:151], v[218:221], v[100:103]
	v_mfma_f32_16x16x32_bf16 v[96:99], v[160:163], v[218:221], v[96:99]
	v_mfma_f32_16x16x32_bf16 v[84:87], v[148:151], v[226:229], v[84:87]
	v_mfma_f32_16x16x32_bf16 v[80:83], v[160:163], v[226:229], v[80:83]
	s_setprio 0
	s_setprio 1
	v_mfma_f32_16x16x32_bf16 v[124:127], v[164:167], v[188:191], v[124:127]
	v_mfma_f32_16x16x32_bf16 v[120:123], v[172:175], v[188:191], v[120:123]
	v_mfma_f32_16x16x32_bf16 v[108:111], v[164:167], v[196:199], v[108:111]
	v_mfma_f32_16x16x32_bf16 v[104:107], v[172:175], v[196:199], v[104:107]
	v_mfma_f32_16x16x32_bf16 v[92:95], v[164:167], v[214:217], v[92:95]
	v_mfma_f32_16x16x32_bf16 v[88:91], v[172:175], v[214:217], v[88:91]
	v_mfma_f32_16x16x32_bf16 v[76:79], v[164:167], v[222:225], v[76:79]
	v_mfma_f32_16x16x32_bf16 v[72:75], v[172:175], v[222:225], v[72:75]
	v_mfma_f32_16x16x32_bf16 v[124:127], v[168:171], v[192:195], v[124:127]
	v_mfma_f32_16x16x32_bf16 v[120:123], v[184:187], v[192:195], v[120:123]
	v_mfma_f32_16x16x32_bf16 v[108:111], v[168:171], v[200:203], v[108:111]
	v_mfma_f32_16x16x32_bf16 v[104:107], v[184:187], v[200:203], v[104:107]
	v_mfma_f32_16x16x32_bf16 v[92:95], v[168:171], v[218:221], v[92:95]
	v_mfma_f32_16x16x32_bf16 v[88:91], v[184:187], v[218:221], v[88:91]
	v_mfma_f32_16x16x32_bf16 v[76:79], v[168:171], v[226:229], v[76:79]
	v_mfma_f32_16x16x32_bf16 v[72:75], v[184:187], v[226:229], v[72:75]
	s_setprio 0
	s_barrier
	s_add_u32 s98, s44, s22
	s_addc_u32 s99, s45, s23
	s_add_u32 s100, s46, s22
	s_addc_u32 s101, s47, s23
	s_add_i32 s36, s72, s20
	s_mov_b32 m0, s36
	ds_read_b128 v[188:191], v155 offset:16384
	ds_read_b128 v[192:195], v155 offset:17408
	ds_read_b128 v[196:199], v155 offset:18432
	ds_read_b128 v[200:203], v155 offset:19456
	ds_read_b128 v[214:217], v155 offset:20480
	ds_read_b128 v[218:221], v155 offset:21504
	ds_read_b128 v[222:225], v155 offset:22528
	ds_read_b128 v[226:229], v155 offset:23552
	global_load_lds_dwordx4 v34, s[44:45]
	s_add_i32 m0, s36, 0x2000
	s_add_u32 s36, s44, 0x160000
	s_addc_u32 s37, s45, 0
	s_add_i32 s72, s73, s20
	global_load_lds_dwordx4 v142, s[44:45]
	s_mov_b32 m0, s72
	s_nop 0
	global_load_lds_dwordx4 v34, s[36:37]
	s_add_i32 m0, s72, 0x2000
	s_nop 0
	global_load_lds_dwordx4 v142, s[36:37]
	s_mov_b32 m0, s25
	s_nop 0
	global_load_lds_dwordx4 v14, s[46:47]
	s_mov_b32 m0, s26
	s_nop 0
	global_load_lds_dwordx4 v140, s[46:47]
	s_waitcnt vmcnt(8)
	s_waitcnt lgkmcnt(0)
	s_barrier
	s_setprio 1
	s_waitcnt lgkmcnt(0)
	v_mfma_f32_16x16x32_bf16 v[68:71], v[136:139], v[188:191], v[68:71]
	v_mfma_f32_16x16x32_bf16 v[64:67], v[156:159], v[188:191], v[64:67]
	v_mfma_f32_16x16x32_bf16 v[52:55], v[136:139], v[196:199], v[52:55]
	v_mfma_f32_16x16x32_bf16 v[48:51], v[156:159], v[196:199], v[48:51]
	v_mfma_f32_16x16x32_bf16 v[36:39], v[136:139], v[214:217], v[36:39]
	v_mfma_f32_16x16x32_bf16 v[30:33], v[156:159], v[214:217], v[30:33]
	v_mfma_f32_16x16x32_bf16 v[18:21], v[136:139], v[222:225], v[18:21]
	v_mfma_f32_16x16x32_bf16 v[10:13], v[156:159], v[222:225], v[10:13]
	v_mfma_f32_16x16x32_bf16 v[68:71], v[148:151], v[192:195], v[68:71]
	v_mfma_f32_16x16x32_bf16 v[64:67], v[160:163], v[192:195], v[64:67]
	v_mfma_f32_16x16x32_bf16 v[52:55], v[148:151], v[200:203], v[52:55]
	v_mfma_f32_16x16x32_bf16 v[48:51], v[160:163], v[200:203], v[48:51]
	v_mfma_f32_16x16x32_bf16 v[36:39], v[148:151], v[218:221], v[36:39]
	v_mfma_f32_16x16x32_bf16 v[30:33], v[160:163], v[218:221], v[30:33]
	v_mfma_f32_16x16x32_bf16 v[18:21], v[148:151], v[226:229], v[18:21]
	v_mfma_f32_16x16x32_bf16 v[10:13], v[160:163], v[226:229], v[10:13]
	s_setprio 0
	s_setprio 1
	v_mfma_f32_16x16x32_bf16 v[60:63], v[164:167], v[188:191], v[60:63]
	v_mfma_f32_16x16x32_bf16 v[56:59], v[172:175], v[188:191], v[56:59]
	v_mfma_f32_16x16x32_bf16 v[44:47], v[164:167], v[196:199], v[44:47]
	v_mfma_f32_16x16x32_bf16 v[40:43], v[172:175], v[196:199], v[40:43]
	v_mfma_f32_16x16x32_bf16 v[26:29], v[164:167], v[214:217], v[26:29]
	v_mfma_f32_16x16x32_bf16 v[22:25], v[172:175], v[214:217], v[22:25]
	v_mfma_f32_16x16x32_bf16 v[6:9], v[164:167], v[222:225], v[6:9]
	v_mfma_f32_16x16x32_bf16 v[2:5], v[172:175], v[222:225], v[2:5]
	v_mfma_f32_16x16x32_bf16 v[60:63], v[168:171], v[192:195], v[60:63]
	v_mfma_f32_16x16x32_bf16 v[56:59], v[184:187], v[192:195], v[56:59]
	v_mfma_f32_16x16x32_bf16 v[44:47], v[168:171], v[200:203], v[44:47]
	v_mfma_f32_16x16x32_bf16 v[40:43], v[184:187], v[200:203], v[40:43]
	v_mfma_f32_16x16x32_bf16 v[26:29], v[168:171], v[218:221], v[26:29]
	v_mfma_f32_16x16x32_bf16 v[22:25], v[184:187], v[218:221], v[22:25]
	v_mfma_f32_16x16x32_bf16 v[6:9], v[168:171], v[226:229], v[6:9]
	v_mfma_f32_16x16x32_bf16 v[2:5], v[184:187], v[226:229], v[2:5]
	s_setprio 0
	s_barrier
	s_add_i32 s72, 0, 0x18000
	s_add_i32 s73, 0, 0x1c000
	v_add_u32_e32 v160, s72, v152
	v_add_u32_e32 v183, s73, v152
	s_add_u32 s36, s46, 0x160000
	s_addc_u32 s37, s47, 0
	s_mov_b32 m0, s27
	s_nop 0
	global_load_lds_dwordx4 v14, s[36:37]
	s_mov_b32 m0, s31
	s_nop 0
	global_load_lds_dwordx4 v140, s[36:37]
	ds_read_b128 v[136:139], v160
	ds_read_b128 v[148:151], v160 offset:1024
	ds_read_b128 v[156:159], v160 offset:2048
	ds_read_b128 v[160:163], v160 offset:3072
	ds_read_b128 v[164:167], v183
	ds_read_b128 v[168:171], v183 offset:1024
	ds_read_b128 v[172:175], v183 offset:2048
	ds_read_b128 v[184:187], v183 offset:3072
	ds_read_b128 v[188:191], v155 offset:32768
	ds_read_b128 v[192:195], v155 offset:33792
	ds_read_b128 v[196:199], v155 offset:34816
	ds_read_b128 v[200:203], v155 offset:35840
	ds_read_b128 v[214:217], v155 offset:36864
	ds_read_b128 v[218:221], v155 offset:37888
	ds_read_b128 v[222:225], v155 offset:38912
	ds_read_b128 v[226:229], v155 offset:39936
	s_waitcnt vmcnt(8)
	s_waitcnt lgkmcnt(0)
	s_barrier
	s_setprio 1
	s_waitcnt lgkmcnt(0)
	v_mfma_f32_16x16x32_bf16 v[132:135], v[136:139], v[188:191], v[132:135]
	v_mfma_f32_16x16x32_bf16 v[128:131], v[156:159], v[188:191], v[128:131]
	v_mfma_f32_16x16x32_bf16 v[116:119], v[136:139], v[196:199], v[116:119]
	v_mfma_f32_16x16x32_bf16 v[112:115], v[156:159], v[196:199], v[112:115]
	v_mfma_f32_16x16x32_bf16 v[100:103], v[136:139], v[214:217], v[100:103]
	v_mfma_f32_16x16x32_bf16 v[96:99], v[156:159], v[214:217], v[96:99]
	v_mfma_f32_16x16x32_bf16 v[84:87], v[136:139], v[222:225], v[84:87]
	v_mfma_f32_16x16x32_bf16 v[80:83], v[156:159], v[222:225], v[80:83]
	v_mfma_f32_16x16x32_bf16 v[132:135], v[148:151], v[192:195], v[132:135]
	v_mfma_f32_16x16x32_bf16 v[128:131], v[160:163], v[192:195], v[128:131]
	v_mfma_f32_16x16x32_bf16 v[116:119], v[148:151], v[200:203], v[116:119]
	v_mfma_f32_16x16x32_bf16 v[112:115], v[160:163], v[200:203], v[112:115]
	v_mfma_f32_16x16x32_bf16 v[100:103], v[148:151], v[218:221], v[100:103]
	v_mfma_f32_16x16x32_bf16 v[96:99], v[160:163], v[218:221], v[96:99]
	v_mfma_f32_16x16x32_bf16 v[84:87], v[148:151], v[226:229], v[84:87]
	v_mfma_f32_16x16x32_bf16 v[80:83], v[160:163], v[226:229], v[80:83]
	s_setprio 0
	s_setprio 1
	v_mfma_f32_16x16x32_bf16 v[124:127], v[164:167], v[188:191], v[124:127]
	v_mfma_f32_16x16x32_bf16 v[120:123], v[172:175], v[188:191], v[120:123]
	v_mfma_f32_16x16x32_bf16 v[108:111], v[164:167], v[196:199], v[108:111]
	v_mfma_f32_16x16x32_bf16 v[104:107], v[172:175], v[196:199], v[104:107]
	v_mfma_f32_16x16x32_bf16 v[92:95], v[164:167], v[214:217], v[92:95]
	v_mfma_f32_16x16x32_bf16 v[88:91], v[172:175], v[214:217], v[88:91]
	v_mfma_f32_16x16x32_bf16 v[76:79], v[164:167], v[222:225], v[76:79]
	v_mfma_f32_16x16x32_bf16 v[72:75], v[172:175], v[222:225], v[72:75]
	v_mfma_f32_16x16x32_bf16 v[124:127], v[168:171], v[192:195], v[124:127]
	v_mfma_f32_16x16x32_bf16 v[120:123], v[184:187], v[192:195], v[120:123]
	v_mfma_f32_16x16x32_bf16 v[108:111], v[168:171], v[200:203], v[108:111]
	v_mfma_f32_16x16x32_bf16 v[104:107], v[184:187], v[200:203], v[104:107]
	v_mfma_f32_16x16x32_bf16 v[92:95], v[168:171], v[218:221], v[92:95]
	v_mfma_f32_16x16x32_bf16 v[88:91], v[184:187], v[218:221], v[88:91]
	v_mfma_f32_16x16x32_bf16 v[76:79], v[168:171], v[226:229], v[76:79]
	v_mfma_f32_16x16x32_bf16 v[72:75], v[184:187], v[226:229], v[72:75]
	s_setprio 0
	s_barrier
	s_add_i32 s36, s72, s20
	s_mov_b32 m0, s36
	ds_read_b128 v[188:191], v155 offset:49152
	ds_read_b128 v[192:195], v155 offset:50176
	ds_read_b128 v[196:199], v155 offset:51200
	ds_read_b128 v[200:203], v155 offset:52224
	ds_read_b128 v[214:217], v155 offset:53248
	ds_read_b128 v[218:221], v155 offset:54272
	ds_read_b128 v[222:225], v155 offset:55296
	ds_read_b128 v[226:229], v155 offset:56320
	global_load_lds_dwordx4 v34, s[98:99]
	s_add_i32 m0, s36, 0x2000
	s_add_u32 s36, s44, 0x160080
	s_addc_u32 s37, s45, 0
	s_add_i32 s44, s73, s20
	global_load_lds_dwordx4 v142, s[98:99]
	s_mov_b32 m0, s44
	s_nop 0
	global_load_lds_dwordx4 v34, s[36:37]
	s_add_i32 m0, s44, 0x2000
	s_nop 0
	global_load_lds_dwordx4 v142, s[36:37]
	s_mov_b32 m0, s50
	s_nop 0
	global_load_lds_dwordx4 v14, s[100:101]
	s_mov_b32 m0, s51
	s_nop 0
	global_load_lds_dwordx4 v140, s[100:101]
	s_waitcnt vmcnt(8)
	s_waitcnt lgkmcnt(0)
	s_barrier
	s_setprio 1
	s_waitcnt lgkmcnt(0)
	v_mfma_f32_16x16x32_bf16 v[68:71], v[136:139], v[188:191], v[68:71]
	v_mfma_f32_16x16x32_bf16 v[64:67], v[156:159], v[188:191], v[64:67]
	v_mfma_f32_16x16x32_bf16 v[52:55], v[136:139], v[196:199], v[52:55]
	v_mfma_f32_16x16x32_bf16 v[48:51], v[156:159], v[196:199], v[48:51]
	v_mfma_f32_16x16x32_bf16 v[36:39], v[136:139], v[214:217], v[36:39]
	v_mfma_f32_16x16x32_bf16 v[30:33], v[156:159], v[214:217], v[30:33]
	v_mfma_f32_16x16x32_bf16 v[18:21], v[136:139], v[222:225], v[18:21]
	v_mfma_f32_16x16x32_bf16 v[10:13], v[156:159], v[222:225], v[10:13]
	v_mfma_f32_16x16x32_bf16 v[68:71], v[148:151], v[192:195], v[68:71]
	v_mfma_f32_16x16x32_bf16 v[64:67], v[160:163], v[192:195], v[64:67]
	v_mfma_f32_16x16x32_bf16 v[52:55], v[148:151], v[200:203], v[52:55]
	v_mfma_f32_16x16x32_bf16 v[48:51], v[160:163], v[200:203], v[48:51]
	v_mfma_f32_16x16x32_bf16 v[36:39], v[148:151], v[218:221], v[36:39]
	v_mfma_f32_16x16x32_bf16 v[30:33], v[160:163], v[218:221], v[30:33]
	v_mfma_f32_16x16x32_bf16 v[18:21], v[148:151], v[226:229], v[18:21]
	v_mfma_f32_16x16x32_bf16 v[10:13], v[160:163], v[226:229], v[10:13]
	s_setprio 0
	s_setprio 1
	v_mfma_f32_16x16x32_bf16 v[60:63], v[164:167], v[188:191], v[60:63]
	v_mfma_f32_16x16x32_bf16 v[56:59], v[172:175], v[188:191], v[56:59]
	v_mfma_f32_16x16x32_bf16 v[44:47], v[164:167], v[196:199], v[44:47]
	v_mfma_f32_16x16x32_bf16 v[40:43], v[172:175], v[196:199], v[40:43]
	v_mfma_f32_16x16x32_bf16 v[26:29], v[164:167], v[214:217], v[26:29]
	v_mfma_f32_16x16x32_bf16 v[22:25], v[172:175], v[214:217], v[22:25]
	v_mfma_f32_16x16x32_bf16 v[6:9], v[164:167], v[222:225], v[6:9]
	v_mfma_f32_16x16x32_bf16 v[2:5], v[172:175], v[222:225], v[2:5]
	v_mfma_f32_16x16x32_bf16 v[60:63], v[168:171], v[192:195], v[60:63]
	v_mfma_f32_16x16x32_bf16 v[56:59], v[184:187], v[192:195], v[56:59]
	v_mfma_f32_16x16x32_bf16 v[44:47], v[168:171], v[200:203], v[44:47]
	v_mfma_f32_16x16x32_bf16 v[40:43], v[184:187], v[200:203], v[40:43]
	v_mfma_f32_16x16x32_bf16 v[26:29], v[168:171], v[218:221], v[26:29]
	v_mfma_f32_16x16x32_bf16 v[22:25], v[184:187], v[218:221], v[22:25]
	v_mfma_f32_16x16x32_bf16 v[6:9], v[168:171], v[226:229], v[6:9]
	v_mfma_f32_16x16x32_bf16 v[2:5], v[184:187], v[226:229], v[2:5]
	s_setprio 0
	s_barrier
	s_add_u32 s70, s70, 0x100
	s_addc_u32 s71, s71, 0
	s_cmp_ge_i32 vcc_lo, s67
	s_mov_b64 s[36:37], s[42:43]
	s_mov_b32 s44, vcc_lo
	s_cbranch_scc0 .LBB0_1764
	s_mov_b32 s71, 0x200000
	s_and_b64 vcc, exec, s[8:9]
	s_cbranch_vccz .LBB0_1767
